# scan: hand-scheduled compute block + 4-deep staging prefetch; NSA sel loop LDS pipelining; rwkv_prep MFMA operand loads hoisted
# speedup vs baseline: 1.0167x; 1.0167x over previous
; #define MFMA32(a, b, c) __builtin_amdgcn_mfma_f32_32x32x16_bf16((a), (b), (c), 0, 0, 0)
; DI unsigned pack2(float a, float b) { fv2 v = {a, b}; return __builtin_bit_cast(unsigned, __builtin_convertvector(v, bfv2)); }
; DI void rwkv_prep(const Params& p, int l, int item, char* smraw) {
;     ...
;     for (int nt = 0; nt < 2; ++nt) {
;       f32x16 aw, aa, av;
; #pragma unroll
;       for (int e = 0; e < 16; ++e) { aw[e] = 0.f; aa[e] = 0.f; av[e] = 0.f; }
; #pragma unroll
;       for (int s = 0; s < 4; ++s) {
;         const bf16x8 f1 = *(const bf16x8*)(A1 + (32 * tt + r31) * LDT + 16 * s + 8 * h);
;         const bf16x8 f2 = *(const bf16x8*)(A2 + (32 * tt + r31) * LDT + 16 * s + 8 * h);
;         const bf16x8 gw = *(const bf16x8*)(lw2 + (w * 64 + 32 * nt + r31) * 64 + 16 * s + 8 * h);
;         const bf16x8 ga = *(const bf16x8*)(la2 + (w * 64 + 32 * nt + r31) * 64 + 16 * s + 8 * h);
;         aw = MFMA32(gw, f1, aw);
;         aa = MFMA32(ga, f2, aa);
;       }
;       if (l == 1) {
;         f32x16 t1;
; #pragma unroll
;         for (int e = 0; e < 16; ++e) t1[e] = 0.f;
; #pragma unroll
;         for (int s = 0; s < 16; ++s) {
;           const bf16x8 fv = *(const bf16x8*)(A3 + (32 * tt + r31) * 264 + 16 * s + 8 * h);
;           const bf16x8 g1 = *(const bf16x8*)(v1t + r31 * 256 + 16 * s + 8 * h);
;           t1 = MFMA32(g1, fv, t1);
;         }
; #pragma unroll
;         for (int s = 0; s < 2; ++s) {
;           unsigned pk[4];
; #pragma unroll
;           for (int e = 0; e < 4; ++e) pk[e] = pack2(t1[8 * s + 2 * e], t1[8 * s + 2 * e + 1]);
;           const bf16x8 fb = __builtin_bit_cast(bf16x8, make_uint4(pk[0], pk[1], pk[2], pk[3]));
;           const bf16_t* vr = v2t + (w * 64 + 32 * nt + r31) * 32 + 16 * s + 4 * h;
;           const uint2 lo = *(const uint2*)vr; const uint2 hi = *(const uint2*)(vr + 8);
;           const bf16x8 fa = __builtin_bit_cast(bf16x8, make_uint4(lo.x, lo.y, hi.x, hi.y));
;           av = MFMA32(fa, fb, av);
;         }
.LBB0_392:
	v_lshl_or_b32 v0, s4, 12, v97
	v_lshl_add_u64 v[50:51], v[88:89], 0, v[0:1]
	v_lshl_add_u64 v[52:53], v[90:91], 0, v[0:1]
	s_and_b64 vcc, exec, s[8:9]
	s_cbranch_vccz .Lp2_nog
	global_load_dwordx4 v[128:131], v[98:99], off
	global_load_dwordx4 v[132:135], v[98:99], off offset:32
	global_load_dwordx4 v[136:139], v[98:99], off offset:64
	global_load_dwordx4 v[140:143], v[98:99], off offset:96
	global_load_dwordx4 v[144:147], v[98:99], off offset:128
	global_load_dwordx4 v[148:151], v[98:99], off offset:160
	global_load_dwordx4 v[152:155], v[98:99], off offset:192
	global_load_dwordx4 v[156:159], v[98:99], off offset:224
	global_load_dwordx4 v[160:163], v[98:99], off offset:256
	global_load_dwordx4 v[164:167], v[98:99], off offset:288
	global_load_dwordx4 v[168:171], v[98:99], off offset:320
	global_load_dwordx4 v[172:175], v[98:99], off offset:352
	global_load_dwordx4 v[176:179], v[98:99], off offset:384
	global_load_dwordx4 v[180:183], v[98:99], off offset:416
	global_load_dwordx4 v[184:187], v[98:99], off offset:448
	global_load_dwordx4 v[188:191], v[98:99], off offset:480
.Lp2_nog:
	ds_read_b128 v[18:21], v86 offset:9216
	global_load_dwordx4 v[2:5], v[50:51], off
	global_load_dwordx4 v[22:25], v[52:53], off
	ds_read_b128 v[6:9], v86
	ds_read_b128 v[34:37], v86 offset:32
	ds_read_b128 v[38:41], v86 offset:9248
	global_load_dwordx4 v[42:45], v[50:51], off offset:32
	global_load_dwordx4 v[46:49], v[52:53], off offset:32
	global_load_dwordx4 v[192:195], v[50:51], off offset:64
	global_load_dwordx4 v[196:199], v[52:53], off offset:64
	global_load_dwordx4 v[210:213], v[50:51], off offset:96
	global_load_dwordx4 v[214:217], v[52:53], off offset:96
	s_and_b64 vcc, exec, s[8:9]
	s_waitcnt vmcnt(7) lgkmcnt(2)
	v_mfma_f32_32x32x16_bf16 v[2:17], v[2:5], v[6:9], 0
	s_waitcnt vmcnt(6)
	v_mfma_f32_32x32x16_bf16 v[18:33], v[22:25], v[18:21], 0
	s_waitcnt vmcnt(5) lgkmcnt(1)
	v_mfma_f32_32x32x16_bf16 v[2:17], v[42:45], v[34:37], v[2:17]
	s_waitcnt vmcnt(4) lgkmcnt(0)
	v_mfma_f32_32x32x16_bf16 v[18:33], v[46:49], v[38:41], v[18:33]
	ds_read_b128 v[34:37], v86 offset:64
	ds_read_b128 v[38:41], v86 offset:9280
	s_waitcnt vmcnt(3) lgkmcnt(1)
	v_mfma_f32_32x32x16_bf16 v[2:17], v[192:195], v[34:37], v[2:17]
	s_waitcnt vmcnt(2) lgkmcnt(0)
	v_mfma_f32_32x32x16_bf16 v[18:33], v[196:199], v[38:41], v[18:33]
	ds_read_b128 v[34:37], v86 offset:96
	ds_read_b128 v[38:41], v86 offset:9312
	s_waitcnt vmcnt(1) lgkmcnt(1)
	v_mfma_f32_32x32x16_bf16 v[2:17], v[210:213], v[34:37], v[2:17]
	v_mov_b32_e32 v34, 0
	v_mov_b32_e32 v35, 0
	v_mov_b32_e32 v36, 0
	v_mov_b32_e32 v37, 0
	v_mov_b32_e32 v42, 0
	v_mov_b32_e32 v43, 0
	v_mov_b32_e32 v44, 0
	s_waitcnt vmcnt(0) lgkmcnt(0)
	v_mfma_f32_32x32x16_bf16 v[18:33], v[214:217], v[38:41], v[18:33]
	v_mov_b32_e32 v38, 0
	v_mov_b32_e32 v39, 0
	v_mov_b32_e32 v40, 0
	v_mov_b32_e32 v41, 0
	v_mov_b32_e32 v45, 0
	v_mov_b32_e32 v46, 0
	v_mov_b32_e32 v47, 0
	v_mov_b32_e32 v48, 0
	v_mov_b32_e32 v49, 0
	s_cbranch_vccz .LBB0_394
	ds_read_b128 v[38:41], v96 offset:18432
	ds_read_b128 v[58:61], v96 offset:18464
	v_lshl_or_b32 v0, s4, 11, v124
	ds_read_b128 v[34:37], v96 offset:18496
	s_waitcnt lgkmcnt(2)
	v_mfma_f32_32x32x16_bf16 v[42:57], v[128:131], v[38:41], 0
	ds_read_b128 v[38:41], v96 offset:18528
	s_waitcnt lgkmcnt(1)
	v_mfma_f32_32x32x16_bf16 v[42:57], v[132:135], v[58:61], v[42:57]
	v_lshl_add_u64 v[58:59], v[100:101], 0, v[0:1]
	s_waitcnt lgkmcnt(1)
	v_mfma_f32_32x32x16_bf16 v[42:57], v[136:139], v[34:37], v[42:57]
	ds_read_b128 v[34:37], v96 offset:18560
	s_waitcnt lgkmcnt(1)
	v_mfma_f32_32x32x16_bf16 v[42:57], v[140:143], v[38:41], v[42:57]
	ds_read_b128 v[38:41], v96 offset:18592
	s_waitcnt lgkmcnt(1)
	v_mfma_f32_32x32x16_bf16 v[42:57], v[144:147], v[34:37], v[42:57]
	ds_read_b128 v[34:37], v96 offset:18624
	s_waitcnt lgkmcnt(1)
	v_mfma_f32_32x32x16_bf16 v[42:57], v[148:151], v[38:41], v[42:57]
	ds_read_b128 v[38:41], v96 offset:18656
	s_waitcnt lgkmcnt(1)
	v_mfma_f32_32x32x16_bf16 v[42:57], v[152:155], v[34:37], v[42:57]
	ds_read_b128 v[34:37], v96 offset:18688
	s_waitcnt lgkmcnt(1)
	v_mfma_f32_32x32x16_bf16 v[42:57], v[156:159], v[38:41], v[42:57]
	ds_read_b128 v[38:41], v96 offset:18720
	s_waitcnt lgkmcnt(1)
	v_mfma_f32_32x32x16_bf16 v[42:57], v[160:163], v[34:37], v[42:57]
	ds_read_b128 v[34:37], v96 offset:18752
	s_waitcnt lgkmcnt(1)
	v_mfma_f32_32x32x16_bf16 v[42:57], v[164:167], v[38:41], v[42:57]
	ds_read_b128 v[38:41], v96 offset:18784
	s_waitcnt lgkmcnt(1)
	v_mfma_f32_32x32x16_bf16 v[42:57], v[168:171], v[34:37], v[42:57]
	ds_read_b128 v[34:37], v96 offset:18816
	s_waitcnt lgkmcnt(1)
	v_mfma_f32_32x32x16_bf16 v[42:57], v[172:175], v[38:41], v[42:57]
	ds_read_b128 v[38:41], v96 offset:18848
	s_waitcnt lgkmcnt(1)
	v_mfma_f32_32x32x16_bf16 v[42:57], v[176:179], v[34:37], v[42:57]
	ds_read_b128 v[34:37], v96 offset:18880
	s_waitcnt lgkmcnt(1)
	v_mfma_f32_32x32x16_bf16 v[42:57], v[180:183], v[38:41], v[42:57]
	ds_read_b128 v[38:41], v96 offset:18912
	s_waitcnt lgkmcnt(1)
	v_mfma_f32_32x32x16_bf16 v[42:57], v[184:187], v[34:37], v[42:57]
	s_waitcnt lgkmcnt(0)
	v_mfma_f32_32x32x16_bf16 v[42:57], v[188:191], v[38:41], v[42:57]
	global_load_dwordx2 v[38:39], v[58:59], off
	global_load_dwordx2 v[40:41], v[58:59], off offset:16
	s_nop 9
	v_cvt_pk_bf16_f32 v50, v50, v51
	v_cvt_pk_bf16_f32 v51, v52, v53
	v_cvt_pk_bf16_f32 v52, v54, v55
	v_cvt_pk_bf16_f32 v53, v56, v57
	global_load_dwordx2 v[54:55], v[58:59], off offset:32
	global_load_dwordx2 v[56:57], v[58:59], off offset:48
	v_cvt_pk_bf16_f32 v34, v42, v43
	v_cvt_pk_bf16_f32 v35, v44, v45
	v_cvt_pk_bf16_f32 v36, v46, v47
	v_cvt_pk_bf16_f32 v37, v48, v49
	s_waitcnt vmcnt(2)
	s_nop 0
	v_mfma_f32_32x32x16_bf16 v[34:49], v[38:41], v[34:37], 0
	s_waitcnt vmcnt(0)
	v_mfma_f32_32x32x16_bf16 v[34:49], v[54:57], v[50:53], v[34:49]

; DI int tidx() { int t = threadIdx.x; asm volatile("" : "+v"(t)); return t; }
; DI char* WS(const Params&) { return *(char* const __attribute__((address_space(4)))*)(KA() + 8 * 30); }
; DI void rwkv_scan(const Params& p, int item, char* smraw) {
;   const int rg = item & 3, hd = (item >> 2) & 3, b = item >> 4;
;   float* stage = (float*)smraw;
;   float* ypart = (float*)(smraw + 3 * 16 * 384 * 4);
;   const bf16_t* pr = (const bf16_t*)(WS(p) + O_PR) + ((size_t)((b * 4 + hd) * 2048)) * 384;
;   bf16_t* yr = (bf16_t*)(WS(p) + O_YR);
;   const int tid = tidx(), row = (tid >> 4) & 15, kq = tid & 15;
;   const bool comp = tid < 256;
;   const int st_ = tid & 255;
;   fv2 S01 = {0.f, 0.f}, S23 = {0.f, 0.f};
;   uint4 g[3];
;   __syncthreads();
;   if (comp) __builtin_amdgcn_s_setprio(3);
;   if (!comp) {
; #pragma unroll
;     for (int c0 = 0; c0 < 2; ++c0) {
; #pragma unroll
;       for (int i = 0; i < 3; ++i) g[i] = *(const uint4*)(pr + (size_t)c0 * 16 * 384 + (size_t)(st_ + 256 * i) * 8);
; #pragma unroll
;       for (int i = 0; i < 3; ++i) scan_put(g[i], st_ + 256 * i, stage + c0 * 16 * 384);
;     }
; #pragma unroll
;     for (int i = 0; i < 3; ++i) g[i] = *(const uint4*)(pr + (size_t)2 * 16 * 384 + (size_t)(st_ + 256 * i) * 8);
.LBB0_493:
	s_mov_b64 s[2:3], s[12:13]
	s_load_dwordx2 s[2:3], s[2:3], 0xf0
	v_mov_b32_e32 v54, v201
	s_ashr_i32 s22, s20, 4
	v_and_b32_e32 v56, 0xff, v54
	s_movk_i32 s0, 0xff
	s_waitcnt vmcnt(0)
	v_mul_u32_u24_e32 v2, 0x1558, v56
	s_bfe_u32 s10, s20, 0x20002
	s_lshl_b32 s21, s22, 13
	v_cmp_lt_i32_e64 s[36:37], s0, v54
	v_lshlrev_b32_e32 v0, 3, v56
	v_lshlrev_b16_sdwa v14, v228, v2 dst_sel:DWORD dst_unused:UNUSED_PAD src0_sel:DWORD src1_sel:WORD_1
	s_waitcnt lgkmcnt(0)
	s_barrier
	s_and_saveexec_b64 s[4:5], s[36:37]
	s_xor_b64 s[34:35], exec, s[4:5]
	s_cbranch_execz .LBB0_495
	s_lshl_b32 s0, s10, 11
	s_or_b32 s0, s0, s21
	s_mul_hi_i32 s1, s0, 0x300
	s_mulk_i32 s0, 0x300
	s_add_u32 s4, s2, s0
	s_addc_u32 s5, s3, s1
	s_add_u32 s6, s4, 0xc764500
	s_addc_u32 s7, s5, 0
	v_lshlrev_b32_e32 v7, 4, v56
	global_load_dwordx4 v[16:19], v7, s[6:7]
	v_lshlrev_b32_e32 v0, 3, v56
	v_or_b32_e32 v55, 0x800, v0
	v_lshlrev_b32_e32 v6, 1, v55
	global_load_dwordx4 v[20:23], v6, s[6:7]
	v_or_b32_e32 v68, 0x1000, v0
	v_lshlrev_b32_e32 v10, 1, v68
	global_load_dwordx4 v[2:5], v10, s[6:7]
	v_and_b32_e32 v8, 0x180, v14
	v_add_u16_e32 v8, v0, v8
	v_and_b32_e32 v60, 0x1c0, v8
	v_cmp_eq_u16_e32 vcc, 64, v60
	s_add_u32 s6, s4, 0xc767500
	s_addc_u32 s7, s5, 0
	s_add_u32 s4, s4, 0xc76a500
	s_addc_u32 s5, s5, 0
	v_mov_b32_e32 v69, v0
	v_mov_b64_e32 v[58:59], v[0:1]
	s_waitcnt vmcnt(0)
	v_lshlrev_b32_e32 v9, 16, v16
	v_and_b32_e32 v11, 0xffff0000, v16
	v_lshlrev_b32_e32 v16, 16, v17
	v_lshlrev_b32_e32 v12, 16, v18
	v_and_b32_e32 v13, 0xffff0000, v18
	v_sub_f32_e32 v8, 1.0, v9
	v_sub_f32_e32 v18, 1.0, v16
	v_cndmask_b32_e32 v18, v16, v18, vcc
	v_cndmask_b32_e32 v16, v9, v8, vcc
	v_mul_u32_u24_e32 v9, 0xaab, v55
	v_and_b32_e32 v17, 0xffff0000, v17
	v_lshlrev_b16_sdwa v9, v226, v9 dst_sel:DWORD dst_unused:UNUSED_PAD src0_sel:DWORD src1_sel:WORD_1
	v_lshlrev_b32_e32 v14, 16, v19
	v_and_b32_e32 v15, 0xffff0000, v19
	v_sub_f32_e32 v24, 1.0, v11
	v_sub_f32_e32 v19, 1.0, v17
	v_and_b32_e32 v9, 0x180, v9
	v_sub_f32_e32 v25, 1.0, v12
	v_sub_f32_e32 v26, 1.0, v13
	v_sub_f32_e32 v27, 1.0, v14
	v_sub_f32_e32 v28, 1.0, v15
	v_cndmask_b32_e32 v19, v17, v19, vcc
	v_cndmask_b32_e32 v17, v11, v24, vcc
	v_lshl_add_u32 v8, v56, 5, 0
	v_add_u16_e32 v9, v0, v9
	v_cndmask_b32_e32 v15, v15, v28, vcc
	v_cndmask_b32_e32 v14, v14, v27, vcc
	v_cndmask_b32_e32 v13, v13, v26, vcc
	v_cndmask_b32_e32 v12, v12, v25, vcc
	ds_write_b128 v8, v[16:19]
	ds_write_b128 v8, v[12:15] offset:16
	v_lshlrev_b32_e32 v11, 16, v20
	v_and_b32_e32 v16, 0xffff0000, v20
	v_lshlrev_b32_e32 v17, 16, v21
	v_and_b32_e32 v18, 0xffff0000, v21
	v_and_b32_e32 v61, 0x1c0, v9
	v_cmp_eq_u16_e64 s[38:39], 64, v61
	v_sub_f32_e32 v9, 1.0, v11
	v_sub_f32_e32 v20, 1.0, v16
	v_sub_f32_e32 v21, 1.0, v17
	v_sub_f32_e32 v19, 1.0, v18
	v_cndmask_b32_e64 v19, v18, v19, s[38:39]
	v_cndmask_b32_e64 v18, v17, v21, s[38:39]
	v_cndmask_b32_e64 v17, v16, v20, s[38:39]
	v_cndmask_b32_e64 v16, v11, v9, s[38:39]
	v_mul_u32_u24_e32 v9, 0xaab, v68
	v_lshlrev_b32_e32 v12, 16, v22
	v_and_b32_e32 v13, 0xffff0000, v22
	v_lshlrev_b32_e32 v14, 16, v23
	v_lshlrev_b16_sdwa v9, v226, v9 dst_sel:DWORD dst_unused:UNUSED_PAD src0_sel:DWORD src1_sel:WORD_1
	v_and_b32_e32 v15, 0xffff0000, v23
	v_sub_f32_e32 v22, 1.0, v12
	v_sub_f32_e32 v23, 1.0, v13
	v_sub_f32_e32 v24, 1.0, v14
	v_and_b32_e32 v9, 0x180, v9
	v_sub_f32_e32 v25, 1.0, v15
	v_cndmask_b32_e64 v14, v14, v24, s[38:39]
	v_cndmask_b32_e64 v13, v13, v23, s[38:39]
	v_cndmask_b32_e64 v12, v12, v22, s[38:39]
	v_add_u16_e32 v9, v0, v9
	v_cndmask_b32_e64 v15, v15, v25, s[38:39]
	ds_write_b128 v8, v[16:19] offset:8192
	ds_write_b128 v8, v[12:15] offset:8208
	v_lshlrev_b32_e32 v11, 16, v2
	v_and_b32_e32 v12, 0xffff0000, v2
	v_lshlrev_b32_e32 v13, 16, v3
	v_and_b32_e32 v14, 0xffff0000, v3
	v_and_b32_e32 v64, 0x1c0, v9
	v_lshlrev_b32_e32 v2, 16, v4
	v_and_b32_e32 v3, 0xffff0000, v4
	v_lshlrev_b32_e32 v4, 16, v5
	v_and_b32_e32 v5, 0xffff0000, v5
	v_cmp_eq_u16_e64 s[40:41], 64, v64
	v_sub_f32_e32 v9, 1.0, v11
	v_sub_f32_e32 v16, 1.0, v12
	v_sub_f32_e32 v17, 1.0, v13
	v_sub_f32_e32 v15, 1.0, v14
	v_sub_f32_e32 v18, 1.0, v2
	v_sub_f32_e32 v19, 1.0, v3
	v_sub_f32_e32 v20, 1.0, v4
	v_sub_f32_e32 v21, 1.0, v5
	v_cndmask_b32_e64 v15, v14, v15, s[40:41]
	v_cndmask_b32_e64 v14, v13, v17, s[40:41]
	v_cndmask_b32_e64 v13, v12, v16, s[40:41]
	v_cndmask_b32_e64 v12, v11, v9, s[40:41]
	v_cndmask_b32_e64 v5, v5, v21, s[40:41]
	v_cndmask_b32_e64 v4, v4, v20, s[40:41]
	v_cndmask_b32_e64 v3, v3, v19, s[40:41]
	v_cndmask_b32_e64 v2, v2, v18, s[40:41]
	ds_write_b128 v8, v[12:15] offset:16384
	ds_write_b128 v8, v[2:5] offset:16400
	global_load_dwordx4 v[2:5], v7, s[6:7]
	global_load_dwordx4 v[12:15], v6, s[6:7]
	global_load_dwordx4 v[16:19], v10, s[6:7]
	s_waitcnt vmcnt(2)
; DI void rwkv_scan(const Params& p, int item, char* smraw) {
;     ...
;       for (int i = 0; i < 3; ++i) scan_put(g[i], st_ + 256 * i, stage + c0 * 16 * 384);
;     }
; #pragma unroll
;     for (int i = 0; i < 3; ++i) g[i] = *(const uint4*)(pr + (size_t)2 * 16 * 384 + (size_t)(st_ + 256 * i) * 8);
;     ...
;       if (ch + 3 < 128) {
;         const bf16_t* src = pr + (size_t)(ch + 3) * 16 * 384;
; #pragma unroll
;         for (int i = 0; i < 3; ++i) g[i] = *(const uint4*)(src + (size_t)(st_ + 256 * i) * 8);
;       }
	v_lshlrev_b32_e32 v9, 16, v2
	v_and_b32_e32 v11, 0xffff0000, v2
	v_lshlrev_b32_e32 v20, 16, v3
	v_and_b32_e32 v21, 0xffff0000, v3
	v_lshlrev_b32_e32 v2, 16, v4
	v_and_b32_e32 v3, 0xffff0000, v4
	v_lshlrev_b32_e32 v4, 16, v5
	v_and_b32_e32 v5, 0xffff0000, v5
	v_sub_f32_e32 v24, 1.0, v9
	v_sub_f32_e32 v25, 1.0, v11
	v_sub_f32_e32 v22, 1.0, v20
	v_sub_f32_e32 v23, 1.0, v21
	v_sub_f32_e32 v26, 1.0, v2
	v_sub_f32_e32 v27, 1.0, v3
	v_sub_f32_e32 v28, 1.0, v4
	v_sub_f32_e32 v29, 1.0, v5
	v_cndmask_b32_e32 v5, v5, v29, vcc
	v_cndmask_b32_e32 v4, v4, v28, vcc
	v_cndmask_b32_e32 v3, v3, v27, vcc
	v_cndmask_b32_e32 v2, v2, v26, vcc
	v_cndmask_b32_e32 v23, v21, v23, vcc
	v_cndmask_b32_e32 v22, v20, v22, vcc
	v_cndmask_b32_e32 v21, v11, v25, vcc
	v_cndmask_b32_e32 v20, v9, v24, vcc
	s_waitcnt vmcnt(1)
	v_lshlrev_b32_e32 v9, 16, v12
	v_and_b32_e32 v11, 0xffff0000, v12
	v_lshlrev_b32_e32 v12, 16, v13
	v_and_b32_e32 v13, 0xffff0000, v13
	ds_write_b128 v8, v[20:23] offset:24576
	ds_write_b128 v8, v[2:5] offset:24592
	v_lshlrev_b32_e32 v2, 16, v14
	v_and_b32_e32 v3, 0xffff0000, v14
	v_lshlrev_b32_e32 v4, 16, v15
	v_and_b32_e32 v5, 0xffff0000, v15
	v_sub_f32_e32 v20, 1.0, v9
	v_sub_f32_e32 v21, 1.0, v11
	v_sub_f32_e32 v14, 1.0, v12
	v_sub_f32_e32 v15, 1.0, v13
	v_sub_f32_e32 v22, 1.0, v2
	v_sub_f32_e32 v23, 1.0, v3
	v_sub_f32_e32 v24, 1.0, v4
	v_sub_f32_e32 v25, 1.0, v5
	v_cndmask_b32_e64 v15, v13, v15, s[38:39]
	v_cndmask_b32_e64 v14, v12, v14, s[38:39]
	v_cndmask_b32_e64 v13, v11, v21, s[38:39]
	v_cndmask_b32_e64 v12, v9, v20, s[38:39]
	v_cndmask_b32_e64 v5, v5, v25, s[38:39]
	v_cndmask_b32_e64 v4, v4, v24, s[38:39]
	v_cndmask_b32_e64 v3, v3, v23, s[38:39]
	v_cndmask_b32_e64 v2, v2, v22, s[38:39]
	ds_write_b128 v8, v[12:15] offset:32768
	ds_write_b128 v8, v[2:5] offset:32784
	s_waitcnt vmcnt(0)
	v_lshlrev_b32_e32 v9, 16, v16
	v_and_b32_e32 v11, 0xffff0000, v16
	v_lshlrev_b32_e32 v12, 16, v17
	v_and_b32_e32 v13, 0xffff0000, v17
	v_lshlrev_b32_e32 v2, 16, v18
	v_and_b32_e32 v3, 0xffff0000, v18
	v_lshlrev_b32_e32 v4, 16, v19
	v_and_b32_e32 v5, 0xffff0000, v19
	v_sub_f32_e32 v16, 1.0, v9
	v_sub_f32_e32 v17, 1.0, v11
	v_sub_f32_e32 v14, 1.0, v12
	v_sub_f32_e32 v15, 1.0, v13
	v_sub_f32_e32 v18, 1.0, v2
	v_sub_f32_e32 v19, 1.0, v3
	v_sub_f32_e32 v20, 1.0, v4
	v_sub_f32_e32 v21, 1.0, v5
	v_cndmask_b32_e64 v15, v13, v15, s[40:41]
	v_cndmask_b32_e64 v14, v12, v14, s[40:41]
	v_cndmask_b32_e64 v13, v11, v17, s[40:41]
	v_cndmask_b32_e64 v12, v9, v16, s[40:41]
	v_cndmask_b32_e64 v5, v5, v21, s[40:41]
	v_cndmask_b32_e64 v4, v4, v20, s[40:41]
	v_cndmask_b32_e64 v3, v3, v19, s[40:41]
	v_cndmask_b32_e64 v2, v2, v18, s[40:41]
	ds_write_b128 v8, v[12:15] offset:40960
	ds_write_b128 v8, v[2:5] offset:40976
	s_add_u32 s98, s4, 0x3000
	s_addc_u32 s99, s5, 0
	global_load_dwordx4 v[130:133], v7, s[98:99]
	global_load_dwordx4 v[134:137], v6, s[98:99]
	global_load_dwordx4 v[138:141], v10, s[98:99]
	s_add_u32 s98, s4, 0x6000
	s_addc_u32 s99, s5, 0
	global_load_dwordx4 v[142:145], v7, s[98:99]
	global_load_dwordx4 v[146:149], v6, s[98:99]
	global_load_dwordx4 v[150:153], v10, s[98:99]
	s_add_u32 s98, s4, 0x9000
	s_addc_u32 s99, s5, 0
	global_load_dwordx4 v[154:157], v7, s[98:99]
	global_load_dwordx4 v[158:161], v6, s[98:99]
	global_load_dwordx4 v[162:165], v10, s[98:99]
	global_load_dwordx4 v[2:5], v7, s[4:5]
	s_nop 0
	global_load_dwordx4 v[6:9], v6, s[4:5]
	s_nop 0
	global_load_dwordx4 v[10:13], v10, s[4:5]

; DI void rwkv_scan(const Params& p, int item, char* smraw) {
;     ...
;       if (ch + 2 < 128) {
;         int nb = cur + 2; if (nb >= 3) nb -= 3;
;         float* dst = stage + nb * 16 * 384;
; #pragma unroll
;         for (int i = 0; i < 3; ++i) scan_put(g[i], st_ + 256 * i, dst);
.LBB0_502:
	s_cmpk_gt_u32 s22, 0x7d
	s_cbranch_scc1 .LBB0_506
	s_cmp_gt_i32 s10, 0
	s_cselect_b32 s0, -1, 2
	s_add_i32 s0, s0, s10
	s_mulk_i32 s0, 0x6000
	s_cmp_eq_u32 s22, 0
	s_cbranch_scc1 .Lst_w0
	s_cmpk_gt_u32 s22, 0x7a
	s_cbranch_scc1 .Lst_w0
	s_waitcnt vmcnt(13)
	s_branch .Lst_wd

; DI void rwkv_scan(const Params& p, int item, char* smraw) {
;     ...
;       if (ch + 2 < 128) {
;         int nb = cur + 2; if (nb >= 3) nb -= 3;
;         float* dst = stage + nb * 16 * 384;
; #pragma unroll
;         for (int i = 0; i < 3; ++i) scan_put(g[i], st_ + 256 * i, dst);
;       }
;       if (ch + 3 < 128) {
;         const bf16_t* src = pr + (size_t)(ch + 3) * 16 * 384;
; #pragma unroll
;         for (int i = 0; i < 3; ++i) g[i] = *(const uint4*)(src + (size_t)(st_ + 256 * i) * 8);
;       }
.Lst_wd:
	s_and_b32 s1, s22, 3
	s_cmp_eq_u32 s1, 1
	s_cbranch_scc1 .Lst_put1
	s_cmp_eq_u32 s1, 2
	s_cbranch_scc1 .Lst_put2
	s_cmp_eq_u32 s1, 3
	s_cbranch_scc1 .Lst_put3
	v_lshlrev_b32_e32 v80, 16, v2
	v_and_b32_e32 v81, 0xffff0000, v2
	v_lshlrev_b32_e32 v82, 16, v3
	v_and_b32_e32 v83, 0xffff0000, v3
	v_lshlrev_b32_e32 v76, 16, v4
	v_and_b32_e32 v77, 0xffff0000, v4
	v_lshlrev_b32_e32 v78, 16, v5
	v_and_b32_e32 v79, 0xffff0000, v5
	v_pk_add_f32 v[84:85], v[80:81], 1.0 op_sel_hi:[1,0] neg_lo:[1,0] neg_hi:[1,0]
	v_pk_add_f32 v[86:87], v[82:83], 1.0 op_sel_hi:[1,0] neg_lo:[1,0] neg_hi:[1,0]
	v_pk_add_f32 v[88:89], v[76:77], 1.0 op_sel_hi:[1,0] neg_lo:[1,0] neg_hi:[1,0]
	v_pk_add_f32 v[90:91], v[78:79], 1.0 op_sel_hi:[1,0] neg_lo:[1,0] neg_hi:[1,0]
	v_cndmask_b32_e64 v83, v83, v87, s[38:39]
	v_cndmask_b32_e64 v82, v82, v86, s[38:39]
	v_cndmask_b32_e64 v81, v81, v85, s[38:39]
	v_cndmask_b32_e64 v80, v80, v84, s[38:39]
	v_lshl_add_u32 v61, v69, 2, s0
	v_cndmask_b32_e64 v79, v79, v91, s[38:39]
	v_cndmask_b32_e64 v77, v77, v89, s[38:39]
	v_cndmask_b32_e64 v78, v78, v90, s[38:39]
	v_cndmask_b32_e64 v76, v76, v88, s[38:39]
	ds_write_b128 v61, v[80:83]
	ds_write_b128 v61, v[76:79] offset:16
	v_lshlrev_b32_e32 v80, 16, v6
	v_and_b32_e32 v81, 0xffff0000, v6
	v_lshlrev_b32_e32 v82, 16, v7
	v_and_b32_e32 v83, 0xffff0000, v7
	v_lshlrev_b32_e32 v76, 16, v8
	v_and_b32_e32 v77, 0xffff0000, v8
	v_lshlrev_b32_e32 v78, 16, v9
	v_and_b32_e32 v79, 0xffff0000, v9
	v_pk_add_f32 v[84:85], v[80:81], 1.0 op_sel_hi:[1,0] neg_lo:[1,0] neg_hi:[1,0]
	v_pk_add_f32 v[86:87], v[82:83], 1.0 op_sel_hi:[1,0] neg_lo:[1,0] neg_hi:[1,0]
	v_pk_add_f32 v[88:89], v[76:77], 1.0 op_sel_hi:[1,0] neg_lo:[1,0] neg_hi:[1,0]
	v_pk_add_f32 v[90:91], v[78:79], 1.0 op_sel_hi:[1,0] neg_lo:[1,0] neg_hi:[1,0]
	v_cndmask_b32_e64 v83, v83, v87, s[40:41]
	v_cndmask_b32_e64 v82, v82, v86, s[40:41]
	v_cndmask_b32_e64 v81, v81, v85, s[40:41]
	v_cndmask_b32_e64 v80, v80, v84, s[40:41]
	v_lshl_add_u32 v61, v55, 2, s0
	v_cndmask_b32_e64 v79, v79, v91, s[40:41]
	v_cndmask_b32_e64 v77, v77, v89, s[40:41]
	v_cndmask_b32_e64 v78, v78, v90, s[40:41]
	v_cndmask_b32_e64 v76, v76, v88, s[40:41]
	ds_write_b128 v61, v[80:83]
	ds_write_b128 v61, v[76:79] offset:16
	v_lshlrev_b32_e32 v80, 16, v10
	v_and_b32_e32 v81, 0xffff0000, v10
	v_lshlrev_b32_e32 v82, 16, v11
	v_and_b32_e32 v83, 0xffff0000, v11
	v_lshlrev_b32_e32 v76, 16, v12
	v_and_b32_e32 v77, 0xffff0000, v12
	v_lshlrev_b32_e32 v78, 16, v13
	v_and_b32_e32 v79, 0xffff0000, v13
	v_pk_add_f32 v[84:85], v[80:81], 1.0 op_sel_hi:[1,0] neg_lo:[1,0] neg_hi:[1,0]
	v_pk_add_f32 v[86:87], v[82:83], 1.0 op_sel_hi:[1,0] neg_lo:[1,0] neg_hi:[1,0]
	v_pk_add_f32 v[88:89], v[76:77], 1.0 op_sel_hi:[1,0] neg_lo:[1,0] neg_hi:[1,0]
	v_pk_add_f32 v[90:91], v[78:79], 1.0 op_sel_hi:[1,0] neg_lo:[1,0] neg_hi:[1,0]
	v_cndmask_b32_e64 v83, v83, v87, s[42:43]
	v_cndmask_b32_e64 v82, v82, v86, s[42:43]
	v_cndmask_b32_e64 v81, v81, v85, s[42:43]
	v_cndmask_b32_e64 v80, v80, v84, s[42:43]
	v_lshl_add_u32 v61, v68, 2, s0
	v_cndmask_b32_e64 v79, v79, v91, s[42:43]
	v_cndmask_b32_e64 v77, v77, v89, s[42:43]
	v_cndmask_b32_e64 v78, v78, v90, s[42:43]
	v_cndmask_b32_e64 v76, v76, v88, s[42:43]
	ds_write_b128 v61, v[80:83]
	ds_write_b128 v61, v[76:79] offset:16
	s_cmpk_gt_u32 s22, 0x79
	s_cbranch_scc1 .LBB0_506
	s_add_u32 s98, s2, 0xc776500
	s_addc_u32 s99, s3, 0
	v_lshl_add_u64 v[166:167], v[58:59], 0, s[98:99]
	s_add_u32 s98, s98, 0x1000
	s_addc_u32 s99, s99, 0
	v_lshl_add_u64 v[168:169], v[58:59], 0, s[98:99]
	s_add_u32 s98, s98, 0x1000
	s_addc_u32 s99, s99, 0
	v_lshl_add_u64 v[170:171], v[58:59], 0, s[98:99]
	global_load_dwordx4 v[2:5], v[166:167], off
	global_load_dwordx4 v[6:9], v[168:169], off
	global_load_dwordx4 v[10:13], v[170:171], off
	s_branch .LBB0_506
.Lst_put1:
	v_lshlrev_b32_e32 v80, 16, v130
	v_and_b32_e32 v81, 0xffff0000, v130
	v_lshlrev_b32_e32 v82, 16, v131
	v_and_b32_e32 v83, 0xffff0000, v131
	v_lshlrev_b32_e32 v76, 16, v132
	v_and_b32_e32 v77, 0xffff0000, v132
	v_lshlrev_b32_e32 v78, 16, v133
	v_and_b32_e32 v79, 0xffff0000, v133
	v_pk_add_f32 v[84:85], v[80:81], 1.0 op_sel_hi:[1,0] neg_lo:[1,0] neg_hi:[1,0]
	v_pk_add_f32 v[86:87], v[82:83], 1.0 op_sel_hi:[1,0] neg_lo:[1,0] neg_hi:[1,0]
	v_pk_add_f32 v[88:89], v[76:77], 1.0 op_sel_hi:[1,0] neg_lo:[1,0] neg_hi:[1,0]
	v_pk_add_f32 v[90:91], v[78:79], 1.0 op_sel_hi:[1,0] neg_lo:[1,0] neg_hi:[1,0]
	v_cndmask_b32_e64 v83, v83, v87, s[38:39]
	v_cndmask_b32_e64 v82, v82, v86, s[38:39]
	v_cndmask_b32_e64 v81, v81, v85, s[38:39]
	v_cndmask_b32_e64 v80, v80, v84, s[38:39]
	v_lshl_add_u32 v61, v69, 2, s0
	v_cndmask_b32_e64 v79, v79, v91, s[38:39]
	v_cndmask_b32_e64 v77, v77, v89, s[38:39]
	v_cndmask_b32_e64 v78, v78, v90, s[38:39]
	v_cndmask_b32_e64 v76, v76, v88, s[38:39]
	ds_write_b128 v61, v[80:83]
	ds_write_b128 v61, v[76:79] offset:16
	v_lshlrev_b32_e32 v80, 16, v134
	v_and_b32_e32 v81, 0xffff0000, v134
	v_lshlrev_b32_e32 v82, 16, v135
	v_and_b32_e32 v83, 0xffff0000, v135
	v_lshlrev_b32_e32 v76, 16, v136
	v_and_b32_e32 v77, 0xffff0000, v136
	v_lshlrev_b32_e32 v78, 16, v137
	v_and_b32_e32 v79, 0xffff0000, v137
	v_pk_add_f32 v[84:85], v[80:81], 1.0 op_sel_hi:[1,0] neg_lo:[1,0] neg_hi:[1,0]
	v_pk_add_f32 v[86:87], v[82:83], 1.0 op_sel_hi:[1,0] neg_lo:[1,0] neg_hi:[1,0]
	v_pk_add_f32 v[88:89], v[76:77], 1.0 op_sel_hi:[1,0] neg_lo:[1,0] neg_hi:[1,0]
	v_pk_add_f32 v[90:91], v[78:79], 1.0 op_sel_hi:[1,0] neg_lo:[1,0] neg_hi:[1,0]
	v_cndmask_b32_e64 v83, v83, v87, s[40:41]
	v_cndmask_b32_e64 v82, v82, v86, s[40:41]
	v_cndmask_b32_e64 v81, v81, v85, s[40:41]
	v_cndmask_b32_e64 v80, v80, v84, s[40:41]
	v_lshl_add_u32 v61, v55, 2, s0
	v_cndmask_b32_e64 v79, v79, v91, s[40:41]
	v_cndmask_b32_e64 v77, v77, v89, s[40:41]
	v_cndmask_b32_e64 v78, v78, v90, s[40:41]
	v_cndmask_b32_e64 v76, v76, v88, s[40:41]
	ds_write_b128 v61, v[80:83]
	ds_write_b128 v61, v[76:79] offset:16
	v_lshlrev_b32_e32 v80, 16, v138
	v_and_b32_e32 v81, 0xffff0000, v138
	v_lshlrev_b32_e32 v82, 16, v139
	v_and_b32_e32 v83, 0xffff0000, v139
	v_lshlrev_b32_e32 v76, 16, v140
	v_and_b32_e32 v77, 0xffff0000, v140
	v_lshlrev_b32_e32 v78, 16, v141
	v_and_b32_e32 v79, 0xffff0000, v141
	v_pk_add_f32 v[84:85], v[80:81], 1.0 op_sel_hi:[1,0] neg_lo:[1,0] neg_hi:[1,0]
	v_pk_add_f32 v[86:87], v[82:83], 1.0 op_sel_hi:[1,0] neg_lo:[1,0] neg_hi:[1,0]
	v_pk_add_f32 v[88:89], v[76:77], 1.0 op_sel_hi:[1,0] neg_lo:[1,0] neg_hi:[1,0]
	v_pk_add_f32 v[90:91], v[78:79], 1.0 op_sel_hi:[1,0] neg_lo:[1,0] neg_hi:[1,0]
	v_cndmask_b32_e64 v83, v83, v87, s[42:43]
	v_cndmask_b32_e64 v82, v82, v86, s[42:43]
	v_cndmask_b32_e64 v81, v81, v85, s[42:43]
	v_cndmask_b32_e64 v80, v80, v84, s[42:43]
	v_lshl_add_u32 v61, v68, 2, s0
	v_cndmask_b32_e64 v79, v79, v91, s[42:43]
	v_cndmask_b32_e64 v77, v77, v89, s[42:43]
	v_cndmask_b32_e64 v78, v78, v90, s[42:43]
	v_cndmask_b32_e64 v76, v76, v88, s[42:43]
	ds_write_b128 v61, v[80:83]
	ds_write_b128 v61, v[76:79] offset:16
	s_cmpk_gt_u32 s22, 0x79
	s_cbranch_scc1 .LBB0_506
; DI float bflo(unsigned u) { return __uint_as_float(u << 16); }
; DI float bfhi(unsigned u) { return __uint_as_float(u & 0xffff0000u); }
; DI void scan_put(const uint4& g, int idx, float* dstbase) {
;   const int e0 = idx * 8; const int arr = (e0 % 384) >> 6;
;   float f[8] = {bflo(g.x), bfhi(g.x), bflo(g.y), bfhi(g.y), bflo(g.z), bfhi(g.z), bflo(g.w), bfhi(g.w)};
;   if (arr == 1) {
; #pragma unroll
;     for (int e = 0; e < 8; ++e) f[e] = 1.f - f[e];
;   }
;   *(float4*)(dstbase + e0) = make_float4(f[0], f[1], f[2], f[3]);
;   *(float4*)(dstbase + e0 + 4) = make_float4(f[4], f[5], f[6], f[7]);
; }
; DI void rwkv_scan(const Params& p, int item, char* smraw) {
;     ...
;       if (ch + 3 < 128) {
;         const bf16_t* src = pr + (size_t)(ch + 3) * 16 * 384;
; #pragma unroll
;         for (int i = 0; i < 3; ++i) g[i] = *(const uint4*)(src + (size_t)(st_ + 256 * i) * 8);
;       }
	s_add_u32 s98, s2, 0xc776500
	s_addc_u32 s99, s3, 0
	v_lshl_add_u64 v[166:167], v[58:59], 0, s[98:99]
	s_add_u32 s98, s98, 0x1000
	s_addc_u32 s99, s99, 0
	v_lshl_add_u64 v[168:169], v[58:59], 0, s[98:99]
	s_add_u32 s98, s98, 0x1000
	s_addc_u32 s99, s99, 0
	v_lshl_add_u64 v[170:171], v[58:59], 0, s[98:99]
	global_load_dwordx4 v[130:133], v[166:167], off
	global_load_dwordx4 v[134:137], v[168:169], off
	global_load_dwordx4 v[138:141], v[170:171], off
	s_branch .LBB0_506
.Lst_put2:
	v_lshlrev_b32_e32 v80, 16, v142
	v_and_b32_e32 v81, 0xffff0000, v142
	v_lshlrev_b32_e32 v82, 16, v143
	v_and_b32_e32 v83, 0xffff0000, v143
	v_lshlrev_b32_e32 v76, 16, v144
	v_and_b32_e32 v77, 0xffff0000, v144
	v_lshlrev_b32_e32 v78, 16, v145
	v_and_b32_e32 v79, 0xffff0000, v145
	v_pk_add_f32 v[84:85], v[80:81], 1.0 op_sel_hi:[1,0] neg_lo:[1,0] neg_hi:[1,0]
	v_pk_add_f32 v[86:87], v[82:83], 1.0 op_sel_hi:[1,0] neg_lo:[1,0] neg_hi:[1,0]
	v_pk_add_f32 v[88:89], v[76:77], 1.0 op_sel_hi:[1,0] neg_lo:[1,0] neg_hi:[1,0]
	v_pk_add_f32 v[90:91], v[78:79], 1.0 op_sel_hi:[1,0] neg_lo:[1,0] neg_hi:[1,0]
	v_cndmask_b32_e64 v83, v83, v87, s[38:39]
	v_cndmask_b32_e64 v82, v82, v86, s[38:39]
	v_cndmask_b32_e64 v81, v81, v85, s[38:39]
	v_cndmask_b32_e64 v80, v80, v84, s[38:39]
	v_lshl_add_u32 v61, v69, 2, s0
	v_cndmask_b32_e64 v79, v79, v91, s[38:39]
	v_cndmask_b32_e64 v77, v77, v89, s[38:39]
	v_cndmask_b32_e64 v78, v78, v90, s[38:39]
	v_cndmask_b32_e64 v76, v76, v88, s[38:39]
	ds_write_b128 v61, v[80:83]
	ds_write_b128 v61, v[76:79] offset:16
	v_lshlrev_b32_e32 v80, 16, v146
	v_and_b32_e32 v81, 0xffff0000, v146
	v_lshlrev_b32_e32 v82, 16, v147
	v_and_b32_e32 v83, 0xffff0000, v147
	v_lshlrev_b32_e32 v76, 16, v148
	v_and_b32_e32 v77, 0xffff0000, v148
	v_lshlrev_b32_e32 v78, 16, v149
	v_and_b32_e32 v79, 0xffff0000, v149
	v_pk_add_f32 v[84:85], v[80:81], 1.0 op_sel_hi:[1,0] neg_lo:[1,0] neg_hi:[1,0]
	v_pk_add_f32 v[86:87], v[82:83], 1.0 op_sel_hi:[1,0] neg_lo:[1,0] neg_hi:[1,0]
	v_pk_add_f32 v[88:89], v[76:77], 1.0 op_sel_hi:[1,0] neg_lo:[1,0] neg_hi:[1,0]
	v_pk_add_f32 v[90:91], v[78:79], 1.0 op_sel_hi:[1,0] neg_lo:[1,0] neg_hi:[1,0]
	v_cndmask_b32_e64 v83, v83, v87, s[40:41]
	v_cndmask_b32_e64 v82, v82, v86, s[40:41]
	v_cndmask_b32_e64 v81, v81, v85, s[40:41]
	v_cndmask_b32_e64 v80, v80, v84, s[40:41]
	v_lshl_add_u32 v61, v55, 2, s0
	v_cndmask_b32_e64 v79, v79, v91, s[40:41]
	v_cndmask_b32_e64 v77, v77, v89, s[40:41]
	v_cndmask_b32_e64 v78, v78, v90, s[40:41]
	v_cndmask_b32_e64 v76, v76, v88, s[40:41]
	ds_write_b128 v61, v[80:83]
	ds_write_b128 v61, v[76:79] offset:16
	v_lshlrev_b32_e32 v80, 16, v150
	v_and_b32_e32 v81, 0xffff0000, v150
	v_lshlrev_b32_e32 v82, 16, v151
	v_and_b32_e32 v83, 0xffff0000, v151
	v_lshlrev_b32_e32 v76, 16, v152
	v_and_b32_e32 v77, 0xffff0000, v152
	v_lshlrev_b32_e32 v78, 16, v153
	v_and_b32_e32 v79, 0xffff0000, v153
	v_pk_add_f32 v[84:85], v[80:81], 1.0 op_sel_hi:[1,0] neg_lo:[1,0] neg_hi:[1,0]
	v_pk_add_f32 v[86:87], v[82:83], 1.0 op_sel_hi:[1,0] neg_lo:[1,0] neg_hi:[1,0]
	v_pk_add_f32 v[88:89], v[76:77], 1.0 op_sel_hi:[1,0] neg_lo:[1,0] neg_hi:[1,0]
	v_pk_add_f32 v[90:91], v[78:79], 1.0 op_sel_hi:[1,0] neg_lo:[1,0] neg_hi:[1,0]
	v_cndmask_b32_e64 v83, v83, v87, s[42:43]
	v_cndmask_b32_e64 v82, v82, v86, s[42:43]
	v_cndmask_b32_e64 v81, v81, v85, s[42:43]
	v_cndmask_b32_e64 v80, v80, v84, s[42:43]
	v_lshl_add_u32 v61, v68, 2, s0
	v_cndmask_b32_e64 v79, v79, v91, s[42:43]
	v_cndmask_b32_e64 v77, v77, v89, s[42:43]
	v_cndmask_b32_e64 v78, v78, v90, s[42:43]
	v_cndmask_b32_e64 v76, v76, v88, s[42:43]
	ds_write_b128 v61, v[80:83]
	ds_write_b128 v61, v[76:79] offset:16
	s_cmpk_gt_u32 s22, 0x79
	s_cbranch_scc1 .LBB0_506
	s_add_u32 s98, s2, 0xc776500
	s_addc_u32 s99, s3, 0
	v_lshl_add_u64 v[166:167], v[58:59], 0, s[98:99]
	s_add_u32 s98, s98, 0x1000
	s_addc_u32 s99, s99, 0
	v_lshl_add_u64 v[168:169], v[58:59], 0, s[98:99]
	s_add_u32 s98, s98, 0x1000
	s_addc_u32 s99, s99, 0
	v_lshl_add_u64 v[170:171], v[58:59], 0, s[98:99]
	global_load_dwordx4 v[142:145], v[166:167], off
	global_load_dwordx4 v[146:149], v[168:169], off
	global_load_dwordx4 v[150:153], v[170:171], off
	s_branch .LBB0_506
.Lst_put3:
	v_lshlrev_b32_e32 v80, 16, v154
	v_and_b32_e32 v81, 0xffff0000, v154
	v_lshlrev_b32_e32 v82, 16, v155
	v_and_b32_e32 v83, 0xffff0000, v155
	v_lshlrev_b32_e32 v76, 16, v156
	v_and_b32_e32 v77, 0xffff0000, v156
	v_lshlrev_b32_e32 v78, 16, v157
	v_and_b32_e32 v79, 0xffff0000, v157
	v_pk_add_f32 v[84:85], v[80:81], 1.0 op_sel_hi:[1,0] neg_lo:[1,0] neg_hi:[1,0]
	v_pk_add_f32 v[86:87], v[82:83], 1.0 op_sel_hi:[1,0] neg_lo:[1,0] neg_hi:[1,0]
	v_pk_add_f32 v[88:89], v[76:77], 1.0 op_sel_hi:[1,0] neg_lo:[1,0] neg_hi:[1,0]
	v_pk_add_f32 v[90:91], v[78:79], 1.0 op_sel_hi:[1,0] neg_lo:[1,0] neg_hi:[1,0]
	v_cndmask_b32_e64 v83, v83, v87, s[38:39]
	v_cndmask_b32_e64 v82, v82, v86, s[38:39]
	v_cndmask_b32_e64 v81, v81, v85, s[38:39]
	v_cndmask_b32_e64 v80, v80, v84, s[38:39]
	v_lshl_add_u32 v61, v69, 2, s0
	v_cndmask_b32_e64 v79, v79, v91, s[38:39]
	v_cndmask_b32_e64 v77, v77, v89, s[38:39]
	v_cndmask_b32_e64 v78, v78, v90, s[38:39]
	v_cndmask_b32_e64 v76, v76, v88, s[38:39]
	ds_write_b128 v61, v[80:83]
	ds_write_b128 v61, v[76:79] offset:16
	v_lshlrev_b32_e32 v80, 16, v158
	v_and_b32_e32 v81, 0xffff0000, v158
	v_lshlrev_b32_e32 v82, 16, v159
	v_and_b32_e32 v83, 0xffff0000, v159
	v_lshlrev_b32_e32 v76, 16, v160
	v_and_b32_e32 v77, 0xffff0000, v160
	v_lshlrev_b32_e32 v78, 16, v161
	v_and_b32_e32 v79, 0xffff0000, v161
	v_pk_add_f32 v[84:85], v[80:81], 1.0 op_sel_hi:[1,0] neg_lo:[1,0] neg_hi:[1,0]
	v_pk_add_f32 v[86:87], v[82:83], 1.0 op_sel_hi:[1,0] neg_lo:[1,0] neg_hi:[1,0]
; DI void rwkv_scan(const Params& p, int item, char* smraw) {
;     ...
;       int nxt = cur + 1; if (nxt == 3) nxt = 0;
;       const float* st = stage + cur * 16 * 384 + 4 * kq;
;       const float* sv = stage + cur * 16 * 384 + 3 * 64 + 16 * rg + row;
;       const float* stn = stage + nxt * 16 * 384 + 4 * kq;
;       const float* svn = stage + nxt * 16 * 384 + 3 * 64 + 16 * rg + row;
; #pragma unroll
;       for (int s = 0; s < 16; ++s) {
;         float4 cr, cw, ck, ca, cb; float cv;
;         if (s & 1) { cr = Pr1; cw = Pw1; ck = Pk1; ca = Pa1; cb = Pb1; cv = Pv1; }
;         else { cr = Pr0; cw = Pw0; ck = Pk0; ca = Pa0; cb = Pb0; cv = Pv0; }
;         {
;           const float* sp = (s < 14) ? (st + (s + 2) * 384) : (stn + (s - 14) * 384);
;           const float* vp = (s < 14) ? (sv + (s + 2) * 384) : (svn + (s - 14) * 384);
;           if (s & 1) { Pr1 = *(const float4*)(sp + 0 * 64); Pw1 = *(const float4*)(sp + 1 * 64); Pk1 = *(const float4*)(sp + 2 * 64); Pa1 = *(const float4*)(sp + 4 * 64); Pb1 = *(const float4*)(sp + 5 * 64); Pv1 = vp[0]; }
;           else { Pr0 = *(const float4*)(sp + 0 * 64); Pw0 = *(const float4*)(sp + 1 * 64); Pk0 = *(const float4*)(sp + 2 * 64); Pa0 = *(const float4*)(sp + 4 * 64); Pb0 = *(const float4*)(sp + 5 * 64); Pv0 = vp[0]; }
;         }
;         const fv2 a01 = {ca.x, ca.y}, a23 = {ca.z, ca.w}, w01 = {cw.x, cw.y}, w23 = {cw.z, cw.w};
;         const fv2 k01 = {ck.x, ck.y}, k23 = {ck.z, ck.w}, b01 = {cb.x, cb.y}, b23 = {cb.z, cb.w};
;         const fv2 r01 = {cr.x, cr.y}, r23 = {cr.z, cr.w};
;         const fv2 vv = {cv, cv};
;         fv2 pa = S01 * a01; pa = __builtin_elementwise_fma(S23, a23, pa);
;         float sa = pa.x + pa.y;
;         const fv2 t01 = __builtin_elementwise_fma(S01, w01, vv * k01);
;         const fv2 t23 = __builtin_elementwise_fma(S23, w23, vv * k23);
;         sa = row16_sum(sa);
;         const fv2 sav = {sa, sa};
;         S01 = __builtin_elementwise_fma(sav, b01, t01);
;         S23 = __builtin_elementwise_fma(sav, b23, t23);
;         fv2 py = S01 * r01; py = __builtin_elementwise_fma(S23, r23, py);
;     ...
;         for (int i = 0; i < 3; ++i) scan_put(g[i], st_ + 256 * i, dst);
;       }
;       if (ch + 3 < 128) {
;         const bf16_t* src = pr + (size_t)(ch + 3) * 16 * 384;
; #pragma unroll
;         for (int i = 0; i < 3; ++i) g[i] = *(const uint4*)(src + (size_t)(st_ + 256 * i) * 8);
	v_pk_add_f32 v[88:89], v[76:77], 1.0 op_sel_hi:[1,0] neg_lo:[1,0] neg_hi:[1,0]
	v_pk_add_f32 v[90:91], v[78:79], 1.0 op_sel_hi:[1,0] neg_lo:[1,0] neg_hi:[1,0]
	v_cndmask_b32_e64 v83, v83, v87, s[40:41]
	v_cndmask_b32_e64 v82, v82, v86, s[40:41]
	v_cndmask_b32_e64 v81, v81, v85, s[40:41]
	v_cndmask_b32_e64 v80, v80, v84, s[40:41]
	v_lshl_add_u32 v61, v55, 2, s0
	v_cndmask_b32_e64 v79, v79, v91, s[40:41]
	v_cndmask_b32_e64 v77, v77, v89, s[40:41]
	v_cndmask_b32_e64 v78, v78, v90, s[40:41]
	v_cndmask_b32_e64 v76, v76, v88, s[40:41]
	ds_write_b128 v61, v[80:83]
	ds_write_b128 v61, v[76:79] offset:16
	v_lshlrev_b32_e32 v80, 16, v162
	v_and_b32_e32 v81, 0xffff0000, v162
	v_lshlrev_b32_e32 v82, 16, v163
	v_and_b32_e32 v83, 0xffff0000, v163
	v_lshlrev_b32_e32 v76, 16, v164
	v_and_b32_e32 v77, 0xffff0000, v164
	v_lshlrev_b32_e32 v78, 16, v165
	v_and_b32_e32 v79, 0xffff0000, v165
	v_pk_add_f32 v[84:85], v[80:81], 1.0 op_sel_hi:[1,0] neg_lo:[1,0] neg_hi:[1,0]
	v_pk_add_f32 v[86:87], v[82:83], 1.0 op_sel_hi:[1,0] neg_lo:[1,0] neg_hi:[1,0]
	v_pk_add_f32 v[88:89], v[76:77], 1.0 op_sel_hi:[1,0] neg_lo:[1,0] neg_hi:[1,0]
	v_pk_add_f32 v[90:91], v[78:79], 1.0 op_sel_hi:[1,0] neg_lo:[1,0] neg_hi:[1,0]
	v_cndmask_b32_e64 v83, v83, v87, s[42:43]
	v_cndmask_b32_e64 v82, v82, v86, s[42:43]
	v_cndmask_b32_e64 v81, v81, v85, s[42:43]
	v_cndmask_b32_e64 v80, v80, v84, s[42:43]
	v_lshl_add_u32 v61, v68, 2, s0
	v_cndmask_b32_e64 v79, v79, v91, s[42:43]
	v_cndmask_b32_e64 v77, v77, v89, s[42:43]
	v_cndmask_b32_e64 v78, v78, v90, s[42:43]
	v_cndmask_b32_e64 v76, v76, v88, s[42:43]
	ds_write_b128 v61, v[80:83]
	ds_write_b128 v61, v[76:79] offset:16
	s_cmpk_gt_u32 s22, 0x79
	s_cbranch_scc1 .LBB0_506
	s_add_u32 s98, s2, 0xc776500
	s_addc_u32 s99, s3, 0
	v_lshl_add_u64 v[166:167], v[58:59], 0, s[98:99]
	s_add_u32 s98, s98, 0x1000
	s_addc_u32 s99, s99, 0
	v_lshl_add_u64 v[168:169], v[58:59], 0, s[98:99]
	s_add_u32 s98, s98, 0x1000
	s_addc_u32 s99, s99, 0
	v_lshl_add_u64 v[170:171], v[58:59], 0, s[98:99]
	global_load_dwordx4 v[154:157], v[166:167], off
	global_load_dwordx4 v[158:161], v[168:169], off
	global_load_dwordx4 v[162:165], v[170:171], off
.LBB0_506:
	s_andn2_saveexec_b64 s[4:5], s[4:5]
	s_cbranch_execz .LBB0_498
	s_mul_i32 s1, s10, 0x6000
	s_lshl_b32 s11, s6, 2
	v_lshlrev_b32_e32 v124, 2, v71
	v_lshlrev_b32_e32 v125, 2, v70
	s_add_i32 s0, s1, s11
	v_mov_b32_e32 v126, v124
	v_mov_b32_e32 v127, v125
	v_add_u32_e32 v124, s1, v124
	v_add_u32_e32 v125, s0, v125
	s_add_i32 s0, s10, 1
	s_cmp_lg_u32 s0, 3
	s_cselect_b32 s0, s0, 0
	s_mul_i32 s0, s0, 0x6000
	v_add_u32_e32 v126, s0, v126
	s_add_i32 s0, s0, s11
	v_add_u32_e32 v127, s0, v127
	s_add_i32 s0, s21, 0x1000
	s_and_b32 s0, s0, 0x1000
	v_lshl_add_u32 v128, s0, 2, v74
	v_pk_mul_f32 v[118:119], v[64:65], v[26:27]
	v_pk_mul_f32 v[22:23], v[22:23], v[62:63] op_sel_hi:[1,0]
	v_pk_fma_f32 v[118:119], v[66:67], v[28:29], v[118:119]
	v_pk_mul_f32 v[24:25], v[24:25], v[62:63] op_sel_hi:[1,0]
	v_pk_fma_f32 v[18:19], v[64:65], v[18:19], v[22:23]
	v_add_f32_e32 v118, v118, v119
	v_pk_fma_f32 v[20:21], v[66:67], v[20:21], v[24:25]
	ds_read2st64_b32 v[116:117], v125 offset0:15 offset1:21
	v_add_f32_dpp v118, v118, v118 quad_perm:[1,0,3,2] row_mask:0xf bank_mask:0xf bound_ctrl:1
	ds_read_b128 v[88:91], v124 offset:4096
	ds_read_b128 v[84:87], v124 offset:3584
	v_add_f32_dpp v118, v118, v118 quad_perm:[2,3,0,1] row_mask:0xf bank_mask:0xf bound_ctrl:1
	ds_read_b128 v[80:83], v124 offset:3328
	ds_read_b128 v[92:95], v124 offset:4352
	v_add_f32_dpp v118, v118, v118 row_half_mirror row_mask:0xf bank_mask:0xf bound_ctrl:1
	ds_read_b128 v[76:79], v124 offset:3072
	s_nop 0
	v_add_f32_dpp v118, v118, v118 row_mirror row_mask:0xf bank_mask:0xf bound_ctrl:1
	v_pk_fma_f32 v[64:65], v[118:119], v[30:31], v[18:19] op_sel_hi:[0,1,1]
	v_pk_fma_f32 v[66:67], v[118:119], v[32:33], v[20:21] op_sel_hi:[0,1,1]
	v_pk_mul_f32 v[118:119], v[64:65], v[50:51]
	v_pk_mul_f32 v[46:47], v[46:47], v[62:63] op_sel:[0,1] op_sel_hi:[1,1]
	v_pk_fma_f32 v[118:119], v[66:67], v[52:53], v[118:119]
	v_pk_mul_f32 v[48:49], v[48:49], v[62:63] op_sel:[0,1] op_sel_hi:[1,1]
	v_pk_fma_f32 v[42:43], v[64:65], v[42:43], v[46:47]
	v_add_f32_e32 v118, v118, v119
	v_pk_fma_f32 v[44:45], v[66:67], v[44:45], v[48:49]
	v_pk_mul_f32 v[120:121], v[64:65], v[14:15]
	v_add_f32_dpp v118, v118, v118 quad_perm:[1,0,3,2] row_mask:0xf bank_mask:0xf bound_ctrl:1
	v_pk_fma_f32 v[120:121], v[66:67], v[16:17], v[120:121]
	ds_read_b128 v[108:111], v124 offset:5632
	v_add_f32_dpp v118, v118, v118 quad_perm:[2,3,0,1] row_mask:0xf bank_mask:0xf bound_ctrl:1
	v_add_f32_e32 v122, v120, v121
	ds_read_b128 v[104:107], v124 offset:5120
	v_add_f32_dpp v118, v118, v118 row_half_mirror row_mask:0xf bank_mask:0xf bound_ctrl:1
	ds_read_b128 v[100:103], v124 offset:4864
	ds_read_b128 v[112:115], v124 offset:5888
	v_add_f32_dpp v118, v118, v118 row_mirror row_mask:0xf bank_mask:0xf bound_ctrl:1
	v_pk_fma_f32 v[64:65], v[118:119], v[38:39], v[42:43] op_sel_hi:[0,1,1]
	v_pk_fma_f32 v[66:67], v[118:119], v[40:41], v[44:45] op_sel_hi:[0,1,1]
	ds_read_b128 v[96:99], v124 offset:4608
	s_waitcnt lgkmcnt(5)
; DI float row16_sum(float x) { x = dpp_add(x, 0); x = dpp_add(x, 1); x = dpp_add(x, 2); x = dpp_add(x, 3); return x; }
; DI void rwkv_scan(const Params& p, int item, char* smraw) {
;     ...
;       for (int s = 0; s < 16; ++s) {
;         float4 cr, cw, ck, ca, cb; float cv;
;         if (s & 1) { cr = Pr1; cw = Pw1; ck = Pk1; ca = Pa1; cb = Pb1; cv = Pv1; }
;         else { cr = Pr0; cw = Pw0; ck = Pk0; ca = Pa0; cb = Pb0; cv = Pv0; }
;         {
;           const float* sp = (s < 14) ? (st + (s + 2) * 384) : (stn + (s - 14) * 384);
;           const float* vp = (s < 14) ? (sv + (s + 2) * 384) : (svn + (s - 14) * 384);
;           if (s & 1) { Pr1 = *(const float4*)(sp + 0 * 64); Pw1 = *(const float4*)(sp + 1 * 64); Pk1 = *(const float4*)(sp + 2 * 64); Pa1 = *(const float4*)(sp + 4 * 64); Pb1 = *(const float4*)(sp + 5 * 64); Pv1 = vp[0]; }
;           else { Pr0 = *(const float4*)(sp + 0 * 64); Pw0 = *(const float4*)(sp + 1 * 64); Pk0 = *(const float4*)(sp + 2 * 64); Pa0 = *(const float4*)(sp + 4 * 64); Pb0 = *(const float4*)(sp + 5 * 64); Pv0 = vp[0]; }
;         }
;         const fv2 a01 = {ca.x, ca.y}, a23 = {ca.z, ca.w}, w01 = {cw.x, cw.y}, w23 = {cw.z, cw.w};
;         const fv2 k01 = {ck.x, ck.y}, k23 = {ck.z, ck.w}, b01 = {cb.x, cb.y}, b23 = {cb.z, cb.w};
;         const fv2 r01 = {cr.x, cr.y}, r23 = {cr.z, cr.w};
;         const fv2 vv = {cv, cv};
;         fv2 pa = S01 * a01; pa = __builtin_elementwise_fma(S23, a23, pa);
;         float sa = pa.x + pa.y;
;         const fv2 t01 = __builtin_elementwise_fma(S01, w01, vv * k01);
;         const fv2 t23 = __builtin_elementwise_fma(S23, w23, vv * k23);
;         sa = row16_sum(sa);
;         const fv2 sav = {sa, sa};
;         S01 = __builtin_elementwise_fma(sav, b01, t01);
;         S23 = __builtin_elementwise_fma(sav, b23, t23);
;         fv2 py = S01 * r01; py = __builtin_elementwise_fma(S23, r23, py);
;         ypart[(ch & 1) * 4096 + s * 256 + tid] = py.x + py.y;
	v_pk_mul_f32 v[118:119], v[64:65], v[88:89]
	v_pk_mul_f32 v[84:85], v[84:85], v[116:117] op_sel_hi:[1,0]
	v_pk_fma_f32 v[118:119], v[66:67], v[90:91], v[118:119]
	v_pk_mul_f32 v[86:87], v[86:87], v[116:117] op_sel_hi:[1,0]
	v_pk_fma_f32 v[80:81], v[64:65], v[80:81], v[84:85]
	v_add_f32_e32 v118, v118, v119
	v_pk_fma_f32 v[82:83], v[66:67], v[82:83], v[86:87]
	v_pk_mul_f32 v[120:121], v[64:65], v[34:35]
	v_add_f32_dpp v118, v118, v118 quad_perm:[1,0,3,2] row_mask:0xf bank_mask:0xf bound_ctrl:1
	v_pk_fma_f32 v[120:121], v[66:67], v[36:37], v[120:121]
	ds_read2st64_b32 v[62:63], v125 offset0:27 offset1:33
	v_add_f32_dpp v118, v118, v118 quad_perm:[2,3,0,1] row_mask:0xf bank_mask:0xf bound_ctrl:1
	v_add_f32_e32 v123, v120, v121
	ds_read_b128 v[26:29], v124 offset:7168
	v_add_f32_dpp v118, v118, v118 row_half_mirror row_mask:0xf bank_mask:0xf bound_ctrl:1
	ds_read_b128 v[22:25], v124 offset:6656
	ds_read_b128 v[18:21], v124 offset:6400
	v_add_f32_dpp v118, v118, v118 row_mirror row_mask:0xf bank_mask:0xf bound_ctrl:1
	v_pk_fma_f32 v[64:65], v[118:119], v[92:93], v[80:81] op_sel_hi:[0,1,1]
	v_pk_fma_f32 v[66:67], v[118:119], v[94:95], v[82:83] op_sel_hi:[0,1,1]
	ds_read_b128 v[30:33], v124 offset:7424
	ds_read_b128 v[14:17], v124 offset:6144
	ds_write2st64_b32 v128, v122, v123 offset0:0 offset1:4
	s_waitcnt lgkmcnt(7)
	v_pk_mul_f32 v[118:119], v[64:65], v[108:109]
	v_pk_mul_f32 v[104:105], v[104:105], v[116:117] op_sel:[0,1] op_sel_hi:[1,1]
	v_pk_fma_f32 v[118:119], v[66:67], v[110:111], v[118:119]
	v_pk_mul_f32 v[106:107], v[106:107], v[116:117] op_sel:[0,1] op_sel_hi:[1,1]
	v_pk_fma_f32 v[100:101], v[64:65], v[100:101], v[104:105]
	v_add_f32_e32 v118, v118, v119
	v_pk_fma_f32 v[102:103], v[66:67], v[102:103], v[106:107]
	v_pk_mul_f32 v[120:121], v[64:65], v[76:77]
	v_add_f32_dpp v118, v118, v118 quad_perm:[1,0,3,2] row_mask:0xf bank_mask:0xf bound_ctrl:1
	v_pk_fma_f32 v[120:121], v[66:67], v[78:79], v[120:121]
	ds_read_b128 v[50:53], v124 offset:8704
	v_add_f32_dpp v118, v118, v118 quad_perm:[2,3,0,1] row_mask:0xf bank_mask:0xf bound_ctrl:1
	v_add_f32_e32 v122, v120, v121
	ds_read_b128 v[46:49], v124 offset:8192
	v_add_f32_dpp v118, v118, v118 row_half_mirror row_mask:0xf bank_mask:0xf bound_ctrl:1
	ds_read_b128 v[42:45], v124 offset:7936
	ds_read_b128 v[38:41], v124 offset:8960
	v_add_f32_dpp v118, v118, v118 row_mirror row_mask:0xf bank_mask:0xf bound_ctrl:1
	v_pk_fma_f32 v[64:65], v[118:119], v[112:113], v[100:101] op_sel_hi:[0,1,1]
	v_pk_fma_f32 v[66:67], v[118:119], v[114:115], v[102:103] op_sel_hi:[0,1,1]
	ds_read_b128 v[34:37], v124 offset:7680
	s_waitcnt lgkmcnt(6)
	v_pk_mul_f32 v[118:119], v[64:65], v[26:27]
	v_pk_mul_f32 v[22:23], v[22:23], v[62:63] op_sel_hi:[1,0]
	v_pk_fma_f32 v[118:119], v[66:67], v[28:29], v[118:119]
	v_pk_mul_f32 v[24:25], v[24:25], v[62:63] op_sel_hi:[1,0]
	v_pk_fma_f32 v[18:19], v[64:65], v[18:19], v[22:23]
	v_add_f32_e32 v118, v118, v119
	v_pk_fma_f32 v[20:21], v[66:67], v[20:21], v[24:25]
	v_pk_mul_f32 v[120:121], v[64:65], v[96:97]
	v_add_f32_dpp v118, v118, v118 quad_perm:[1,0,3,2] row_mask:0xf bank_mask:0xf bound_ctrl:1
	v_pk_fma_f32 v[120:121], v[66:67], v[98:99], v[120:121]
	ds_read2st64_b32 v[116:117], v125 offset0:39 offset1:45
	v_add_f32_dpp v118, v118, v118 quad_perm:[2,3,0,1] row_mask:0xf bank_mask:0xf bound_ctrl:1
	v_add_f32_e32 v123, v120, v121
	ds_read_b128 v[88:91], v124 offset:10240
	v_add_f32_dpp v118, v118, v118 row_half_mirror row_mask:0xf bank_mask:0xf bound_ctrl:1
	ds_read_b128 v[84:87], v124 offset:9728
	ds_read_b128 v[80:83], v124 offset:9472
	v_add_f32_dpp v118, v118, v118 row_mirror row_mask:0xf bank_mask:0xf bound_ctrl:1
	v_pk_fma_f32 v[64:65], v[118:119], v[30:31], v[18:19] op_sel_hi:[0,1,1]
	v_pk_fma_f32 v[66:67], v[118:119], v[32:33], v[20:21] op_sel_hi:[0,1,1]
	ds_read_b128 v[92:95], v124 offset:10496
	ds_read_b128 v[76:79], v124 offset:9216
	ds_write2st64_b32 v128, v122, v123 offset0:8 offset1:12
	s_waitcnt lgkmcnt(7)
	v_pk_mul_f32 v[118:119], v[64:65], v[50:51]
	v_pk_mul_f32 v[46:47], v[46:47], v[62:63] op_sel:[0,1] op_sel_hi:[1,1]
	v_pk_fma_f32 v[118:119], v[66:67], v[52:53], v[118:119]
	v_pk_mul_f32 v[48:49], v[48:49], v[62:63] op_sel:[0,1] op_sel_hi:[1,1]
	v_pk_fma_f32 v[42:43], v[64:65], v[42:43], v[46:47]
	v_add_f32_e32 v118, v118, v119
	v_pk_fma_f32 v[44:45], v[66:67], v[44:45], v[48:49]
	v_pk_mul_f32 v[120:121], v[64:65], v[14:15]
	v_add_f32_dpp v118, v118, v118 quad_perm:[1,0,3,2] row_mask:0xf bank_mask:0xf bound_ctrl:1
	v_pk_fma_f32 v[120:121], v[66:67], v[16:17], v[120:121]
	ds_read_b128 v[108:111], v124 offset:11776
	v_add_f32_dpp v118, v118, v118 quad_perm:[2,3,0,1] row_mask:0xf bank_mask:0xf bound_ctrl:1
	v_add_f32_e32 v122, v120, v121
	ds_read_b128 v[104:107], v124 offset:11264
	v_add_f32_dpp v118, v118, v118 row_half_mirror row_mask:0xf bank_mask:0xf bound_ctrl:1
	ds_read_b128 v[100:103], v124 offset:11008
	ds_read_b128 v[112:115], v124 offset:12032
	v_add_f32_dpp v118, v118, v118 row_mirror row_mask:0xf bank_mask:0xf bound_ctrl:1
	v_pk_fma_f32 v[64:65], v[118:119], v[38:39], v[42:43] op_sel_hi:[0,1,1]
	v_pk_fma_f32 v[66:67], v[118:119], v[40:41], v[44:45] op_sel_hi:[0,1,1]
	ds_read_b128 v[96:99], v124 offset:10752
	s_waitcnt lgkmcnt(6)
; DI float row16_sum(float x) { x = dpp_add(x, 0); x = dpp_add(x, 1); x = dpp_add(x, 2); x = dpp_add(x, 3); return x; }
; DI void rwkv_scan(const Params& p, int item, char* smraw) {
;     ...
;       for (int s = 0; s < 16; ++s) {
;         float4 cr, cw, ck, ca, cb; float cv;
;         if (s & 1) { cr = Pr1; cw = Pw1; ck = Pk1; ca = Pa1; cb = Pb1; cv = Pv1; }
;         else { cr = Pr0; cw = Pw0; ck = Pk0; ca = Pa0; cb = Pb0; cv = Pv0; }
;         {
;           const float* sp = (s < 14) ? (st + (s + 2) * 384) : (stn + (s - 14) * 384);
;           const float* vp = (s < 14) ? (sv + (s + 2) * 384) : (svn + (s - 14) * 384);
;           if (s & 1) { Pr1 = *(const float4*)(sp + 0 * 64); Pw1 = *(const float4*)(sp + 1 * 64); Pk1 = *(const float4*)(sp + 2 * 64); Pa1 = *(const float4*)(sp + 4 * 64); Pb1 = *(const float4*)(sp + 5 * 64); Pv1 = vp[0]; }
;           else { Pr0 = *(const float4*)(sp + 0 * 64); Pw0 = *(const float4*)(sp + 1 * 64); Pk0 = *(const float4*)(sp + 2 * 64); Pa0 = *(const float4*)(sp + 4 * 64); Pb0 = *(const float4*)(sp + 5 * 64); Pv0 = vp[0]; }
;         }
;         const fv2 a01 = {ca.x, ca.y}, a23 = {ca.z, ca.w}, w01 = {cw.x, cw.y}, w23 = {cw.z, cw.w};
;         const fv2 k01 = {ck.x, ck.y}, k23 = {ck.z, ck.w}, b01 = {cb.x, cb.y}, b23 = {cb.z, cb.w};
;         const fv2 r01 = {cr.x, cr.y}, r23 = {cr.z, cr.w};
;         const fv2 vv = {cv, cv};
;         fv2 pa = S01 * a01; pa = __builtin_elementwise_fma(S23, a23, pa);
;         float sa = pa.x + pa.y;
;         const fv2 t01 = __builtin_elementwise_fma(S01, w01, vv * k01);
;         const fv2 t23 = __builtin_elementwise_fma(S23, w23, vv * k23);
;         sa = row16_sum(sa);
;         const fv2 sav = {sa, sa};
;         S01 = __builtin_elementwise_fma(sav, b01, t01);
;         S23 = __builtin_elementwise_fma(sav, b23, t23);
;         fv2 py = S01 * r01; py = __builtin_elementwise_fma(S23, r23, py);
;         ypart[(ch & 1) * 4096 + s * 256 + tid] = py.x + py.y;
	v_pk_mul_f32 v[118:119], v[64:65], v[88:89]
	v_pk_mul_f32 v[84:85], v[84:85], v[116:117] op_sel_hi:[1,0]
	v_pk_fma_f32 v[118:119], v[66:67], v[90:91], v[118:119]
	v_pk_mul_f32 v[86:87], v[86:87], v[116:117] op_sel_hi:[1,0]
	v_pk_fma_f32 v[80:81], v[64:65], v[80:81], v[84:85]
	v_add_f32_e32 v118, v118, v119
	v_pk_fma_f32 v[82:83], v[66:67], v[82:83], v[86:87]
	v_pk_mul_f32 v[120:121], v[64:65], v[34:35]
	v_add_f32_dpp v118, v118, v118 quad_perm:[1,0,3,2] row_mask:0xf bank_mask:0xf bound_ctrl:1
	v_pk_fma_f32 v[120:121], v[66:67], v[36:37], v[120:121]
	ds_read2st64_b32 v[62:63], v125 offset0:51 offset1:57
	v_add_f32_dpp v118, v118, v118 quad_perm:[2,3,0,1] row_mask:0xf bank_mask:0xf bound_ctrl:1
	v_add_f32_e32 v123, v120, v121
	ds_read_b128 v[26:29], v124 offset:13312
	v_add_f32_dpp v118, v118, v118 row_half_mirror row_mask:0xf bank_mask:0xf bound_ctrl:1
	ds_read_b128 v[22:25], v124 offset:12800
	ds_read_b128 v[18:21], v124 offset:12544
	v_add_f32_dpp v118, v118, v118 row_mirror row_mask:0xf bank_mask:0xf bound_ctrl:1
	v_pk_fma_f32 v[64:65], v[118:119], v[92:93], v[80:81] op_sel_hi:[0,1,1]
	v_pk_fma_f32 v[66:67], v[118:119], v[94:95], v[82:83] op_sel_hi:[0,1,1]
	ds_read_b128 v[30:33], v124 offset:13568
	ds_read_b128 v[14:17], v124 offset:12288
	ds_write2st64_b32 v128, v122, v123 offset0:16 offset1:20
	s_waitcnt lgkmcnt(7)
	v_pk_mul_f32 v[118:119], v[64:65], v[108:109]
	v_pk_mul_f32 v[104:105], v[104:105], v[116:117] op_sel:[0,1] op_sel_hi:[1,1]
	v_pk_fma_f32 v[118:119], v[66:67], v[110:111], v[118:119]
	v_pk_mul_f32 v[106:107], v[106:107], v[116:117] op_sel:[0,1] op_sel_hi:[1,1]
	v_pk_fma_f32 v[100:101], v[64:65], v[100:101], v[104:105]
	v_add_f32_e32 v118, v118, v119
	v_pk_fma_f32 v[102:103], v[66:67], v[102:103], v[106:107]
	v_pk_mul_f32 v[120:121], v[64:65], v[76:77]
	v_add_f32_dpp v118, v118, v118 quad_perm:[1,0,3,2] row_mask:0xf bank_mask:0xf bound_ctrl:1
	v_pk_fma_f32 v[120:121], v[66:67], v[78:79], v[120:121]
	ds_read_b128 v[50:53], v124 offset:14848
	v_add_f32_dpp v118, v118, v118 quad_perm:[2,3,0,1] row_mask:0xf bank_mask:0xf bound_ctrl:1
	v_add_f32_e32 v122, v120, v121
	ds_read_b128 v[46:49], v124 offset:14336
	v_add_f32_dpp v118, v118, v118 row_half_mirror row_mask:0xf bank_mask:0xf bound_ctrl:1
	ds_read_b128 v[42:45], v124 offset:14080
	ds_read_b128 v[38:41], v124 offset:15104
	v_add_f32_dpp v118, v118, v118 row_mirror row_mask:0xf bank_mask:0xf bound_ctrl:1
	v_pk_fma_f32 v[64:65], v[118:119], v[112:113], v[100:101] op_sel_hi:[0,1,1]
	v_pk_fma_f32 v[66:67], v[118:119], v[114:115], v[102:103] op_sel_hi:[0,1,1]
	ds_read_b128 v[34:37], v124 offset:13824
	s_waitcnt lgkmcnt(6)
	v_pk_mul_f32 v[118:119], v[64:65], v[26:27]
	v_pk_mul_f32 v[22:23], v[22:23], v[62:63] op_sel_hi:[1,0]
	v_pk_fma_f32 v[118:119], v[66:67], v[28:29], v[118:119]
	v_pk_mul_f32 v[24:25], v[24:25], v[62:63] op_sel_hi:[1,0]
	v_pk_fma_f32 v[18:19], v[64:65], v[18:19], v[22:23]
	v_add_f32_e32 v118, v118, v119
	v_pk_fma_f32 v[20:21], v[66:67], v[20:21], v[24:25]
	v_pk_mul_f32 v[120:121], v[64:65], v[96:97]
	v_add_f32_dpp v118, v118, v118 quad_perm:[1,0,3,2] row_mask:0xf bank_mask:0xf bound_ctrl:1
	v_pk_fma_f32 v[120:121], v[66:67], v[98:99], v[120:121]
	ds_read2st64_b32 v[116:117], v125 offset0:63 offset1:69
	v_add_f32_dpp v118, v118, v118 quad_perm:[2,3,0,1] row_mask:0xf bank_mask:0xf bound_ctrl:1
	v_add_f32_e32 v123, v120, v121
	ds_read_b128 v[88:91], v124 offset:16384
	v_add_f32_dpp v118, v118, v118 row_half_mirror row_mask:0xf bank_mask:0xf bound_ctrl:1
	ds_read_b128 v[84:87], v124 offset:15872
	ds_read_b128 v[80:83], v124 offset:15616
	v_add_f32_dpp v118, v118, v118 row_mirror row_mask:0xf bank_mask:0xf bound_ctrl:1
	v_pk_fma_f32 v[64:65], v[118:119], v[30:31], v[18:19] op_sel_hi:[0,1,1]
	v_pk_fma_f32 v[66:67], v[118:119], v[32:33], v[20:21] op_sel_hi:[0,1,1]
	ds_read_b128 v[92:95], v124 offset:16640
	ds_read_b128 v[76:79], v124 offset:15360
	ds_write2st64_b32 v128, v122, v123 offset0:24 offset1:28
	s_waitcnt lgkmcnt(7)
	v_pk_mul_f32 v[118:119], v[64:65], v[50:51]
	v_pk_mul_f32 v[46:47], v[46:47], v[62:63] op_sel:[0,1] op_sel_hi:[1,1]
	v_pk_fma_f32 v[118:119], v[66:67], v[52:53], v[118:119]
	v_pk_mul_f32 v[48:49], v[48:49], v[62:63] op_sel:[0,1] op_sel_hi:[1,1]
	v_pk_fma_f32 v[42:43], v[64:65], v[42:43], v[46:47]
	v_add_f32_e32 v118, v118, v119
	v_pk_fma_f32 v[44:45], v[66:67], v[44:45], v[48:49]
	v_pk_mul_f32 v[120:121], v[64:65], v[14:15]
	v_add_f32_dpp v118, v118, v118 quad_perm:[1,0,3,2] row_mask:0xf bank_mask:0xf bound_ctrl:1
	v_pk_fma_f32 v[120:121], v[66:67], v[16:17], v[120:121]
	ds_read_b128 v[108:111], v124 offset:17920
	v_add_f32_dpp v118, v118, v118 quad_perm:[2,3,0,1] row_mask:0xf bank_mask:0xf bound_ctrl:1
	v_add_f32_e32 v122, v120, v121
	ds_read_b128 v[104:107], v124 offset:17408
	v_add_f32_dpp v118, v118, v118 row_half_mirror row_mask:0xf bank_mask:0xf bound_ctrl:1
	ds_read_b128 v[100:103], v124 offset:17152
	ds_read_b128 v[112:115], v124 offset:18176
	v_add_f32_dpp v118, v118, v118 row_mirror row_mask:0xf bank_mask:0xf bound_ctrl:1
	v_pk_fma_f32 v[64:65], v[118:119], v[38:39], v[42:43] op_sel_hi:[0,1,1]
	v_pk_fma_f32 v[66:67], v[118:119], v[40:41], v[44:45] op_sel_hi:[0,1,1]
	ds_read_b128 v[96:99], v124 offset:16896
	s_waitcnt lgkmcnt(6)
; DI float row16_sum(float x) { x = dpp_add(x, 0); x = dpp_add(x, 1); x = dpp_add(x, 2); x = dpp_add(x, 3); return x; }
; DI void rwkv_scan(const Params& p, int item, char* smraw) {
;     ...
;       for (int s = 0; s < 16; ++s) {
;         float4 cr, cw, ck, ca, cb; float cv;
;         if (s & 1) { cr = Pr1; cw = Pw1; ck = Pk1; ca = Pa1; cb = Pb1; cv = Pv1; }
;         else { cr = Pr0; cw = Pw0; ck = Pk0; ca = Pa0; cb = Pb0; cv = Pv0; }
;         {
;           const float* sp = (s < 14) ? (st + (s + 2) * 384) : (stn + (s - 14) * 384);
;           const float* vp = (s < 14) ? (sv + (s + 2) * 384) : (svn + (s - 14) * 384);
;           if (s & 1) { Pr1 = *(const float4*)(sp + 0 * 64); Pw1 = *(const float4*)(sp + 1 * 64); Pk1 = *(const float4*)(sp + 2 * 64); Pa1 = *(const float4*)(sp + 4 * 64); Pb1 = *(const float4*)(sp + 5 * 64); Pv1 = vp[0]; }
;           else { Pr0 = *(const float4*)(sp + 0 * 64); Pw0 = *(const float4*)(sp + 1 * 64); Pk0 = *(const float4*)(sp + 2 * 64); Pa0 = *(const float4*)(sp + 4 * 64); Pb0 = *(const float4*)(sp + 5 * 64); Pv0 = vp[0]; }
;         }
;         const fv2 a01 = {ca.x, ca.y}, a23 = {ca.z, ca.w}, w01 = {cw.x, cw.y}, w23 = {cw.z, cw.w};
;         const fv2 k01 = {ck.x, ck.y}, k23 = {ck.z, ck.w}, b01 = {cb.x, cb.y}, b23 = {cb.z, cb.w};
;         const fv2 r01 = {cr.x, cr.y}, r23 = {cr.z, cr.w};
;         const fv2 vv = {cv, cv};
;         fv2 pa = S01 * a01; pa = __builtin_elementwise_fma(S23, a23, pa);
;         float sa = pa.x + pa.y;
;         const fv2 t01 = __builtin_elementwise_fma(S01, w01, vv * k01);
;         const fv2 t23 = __builtin_elementwise_fma(S23, w23, vv * k23);
;         sa = row16_sum(sa);
;         const fv2 sav = {sa, sa};
;         S01 = __builtin_elementwise_fma(sav, b01, t01);
;         S23 = __builtin_elementwise_fma(sav, b23, t23);
;         fv2 py = S01 * r01; py = __builtin_elementwise_fma(S23, r23, py);
;         ypart[(ch & 1) * 4096 + s * 256 + tid] = py.x + py.y;
	v_pk_mul_f32 v[118:119], v[64:65], v[88:89]
	v_pk_mul_f32 v[84:85], v[84:85], v[116:117] op_sel_hi:[1,0]
	v_pk_fma_f32 v[118:119], v[66:67], v[90:91], v[118:119]
	v_pk_mul_f32 v[86:87], v[86:87], v[116:117] op_sel_hi:[1,0]
	v_pk_fma_f32 v[80:81], v[64:65], v[80:81], v[84:85]
	v_add_f32_e32 v118, v118, v119
	v_pk_fma_f32 v[82:83], v[66:67], v[82:83], v[86:87]
	v_pk_mul_f32 v[120:121], v[64:65], v[34:35]
	v_add_f32_dpp v118, v118, v118 quad_perm:[1,0,3,2] row_mask:0xf bank_mask:0xf bound_ctrl:1
	v_pk_fma_f32 v[120:121], v[66:67], v[36:37], v[120:121]
	ds_read2st64_b32 v[62:63], v125 offset0:75 offset1:81
	v_add_f32_dpp v118, v118, v118 quad_perm:[2,3,0,1] row_mask:0xf bank_mask:0xf bound_ctrl:1
	v_add_f32_e32 v123, v120, v121
	ds_read_b128 v[26:29], v124 offset:19456
	v_add_f32_dpp v118, v118, v118 row_half_mirror row_mask:0xf bank_mask:0xf bound_ctrl:1
	ds_read_b128 v[22:25], v124 offset:18944
	ds_read_b128 v[18:21], v124 offset:18688
	v_add_f32_dpp v118, v118, v118 row_mirror row_mask:0xf bank_mask:0xf bound_ctrl:1
	v_pk_fma_f32 v[64:65], v[118:119], v[92:93], v[80:81] op_sel_hi:[0,1,1]
	v_pk_fma_f32 v[66:67], v[118:119], v[94:95], v[82:83] op_sel_hi:[0,1,1]
	ds_read_b128 v[30:33], v124 offset:19712
	ds_read_b128 v[14:17], v124 offset:18432
	ds_write2st64_b32 v128, v122, v123 offset0:32 offset1:36
	s_waitcnt lgkmcnt(7)
	v_pk_mul_f32 v[118:119], v[64:65], v[108:109]
	v_pk_mul_f32 v[104:105], v[104:105], v[116:117] op_sel:[0,1] op_sel_hi:[1,1]
	v_pk_fma_f32 v[118:119], v[66:67], v[110:111], v[118:119]
	v_pk_mul_f32 v[106:107], v[106:107], v[116:117] op_sel:[0,1] op_sel_hi:[1,1]
	v_pk_fma_f32 v[100:101], v[64:65], v[100:101], v[104:105]
	v_add_f32_e32 v118, v118, v119
	v_pk_fma_f32 v[102:103], v[66:67], v[102:103], v[106:107]
	v_pk_mul_f32 v[120:121], v[64:65], v[76:77]
	v_add_f32_dpp v118, v118, v118 quad_perm:[1,0,3,2] row_mask:0xf bank_mask:0xf bound_ctrl:1
	v_pk_fma_f32 v[120:121], v[66:67], v[78:79], v[120:121]
	ds_read_b128 v[50:53], v124 offset:20992
	v_add_f32_dpp v118, v118, v118 quad_perm:[2,3,0,1] row_mask:0xf bank_mask:0xf bound_ctrl:1
	v_add_f32_e32 v122, v120, v121
	ds_read_b128 v[46:49], v124 offset:20480
	v_add_f32_dpp v118, v118, v118 row_half_mirror row_mask:0xf bank_mask:0xf bound_ctrl:1
	ds_read_b128 v[42:45], v124 offset:20224
	ds_read_b128 v[38:41], v124 offset:21248
	v_add_f32_dpp v118, v118, v118 row_mirror row_mask:0xf bank_mask:0xf bound_ctrl:1
	v_pk_fma_f32 v[64:65], v[118:119], v[112:113], v[100:101] op_sel_hi:[0,1,1]
	v_pk_fma_f32 v[66:67], v[118:119], v[114:115], v[102:103] op_sel_hi:[0,1,1]
	ds_read_b128 v[34:37], v124 offset:19968
	s_waitcnt lgkmcnt(6)
	v_pk_mul_f32 v[118:119], v[64:65], v[26:27]
	v_pk_mul_f32 v[22:23], v[22:23], v[62:63] op_sel_hi:[1,0]
	v_pk_fma_f32 v[118:119], v[66:67], v[28:29], v[118:119]
	v_pk_mul_f32 v[24:25], v[24:25], v[62:63] op_sel_hi:[1,0]
	v_pk_fma_f32 v[18:19], v[64:65], v[18:19], v[22:23]
	v_add_f32_e32 v118, v118, v119
	v_pk_fma_f32 v[20:21], v[66:67], v[20:21], v[24:25]
	v_pk_mul_f32 v[120:121], v[64:65], v[96:97]
	v_add_f32_dpp v118, v118, v118 quad_perm:[1,0,3,2] row_mask:0xf bank_mask:0xf bound_ctrl:1
	v_pk_fma_f32 v[120:121], v[66:67], v[98:99], v[120:121]
	ds_read2st64_b32 v[116:117], v125 offset0:87 offset1:93
	v_add_f32_dpp v118, v118, v118 quad_perm:[2,3,0,1] row_mask:0xf bank_mask:0xf bound_ctrl:1
	v_add_f32_e32 v123, v120, v121
	ds_read_b128 v[88:91], v124 offset:22528
	v_add_f32_dpp v118, v118, v118 row_half_mirror row_mask:0xf bank_mask:0xf bound_ctrl:1
	ds_read_b128 v[84:87], v124 offset:22016
	ds_read_b128 v[80:83], v124 offset:21760
	v_add_f32_dpp v118, v118, v118 row_mirror row_mask:0xf bank_mask:0xf bound_ctrl:1
	v_pk_fma_f32 v[64:65], v[118:119], v[30:31], v[18:19] op_sel_hi:[0,1,1]
	v_pk_fma_f32 v[66:67], v[118:119], v[32:33], v[20:21] op_sel_hi:[0,1,1]
	ds_read_b128 v[92:95], v124 offset:22784
	ds_read_b128 v[76:79], v124 offset:21504
	ds_write2st64_b32 v128, v122, v123 offset0:40 offset1:44
	s_waitcnt lgkmcnt(7)
; DI float row16_sum(float x) { x = dpp_add(x, 0); x = dpp_add(x, 1); x = dpp_add(x, 2); x = dpp_add(x, 3); return x; }
; DI void rwkv_scan(const Params& p, int item, char* smraw) {
;     ...
;       for (int s = 0; s < 16; ++s) {
;         float4 cr, cw, ck, ca, cb; float cv;
;         if (s & 1) { cr = Pr1; cw = Pw1; ck = Pk1; ca = Pa1; cb = Pb1; cv = Pv1; }
;         else { cr = Pr0; cw = Pw0; ck = Pk0; ca = Pa0; cb = Pb0; cv = Pv0; }
;         {
;           const float* sp = (s < 14) ? (st + (s + 2) * 384) : (stn + (s - 14) * 384);
;           const float* vp = (s < 14) ? (sv + (s + 2) * 384) : (svn + (s - 14) * 384);
;           if (s & 1) { Pr1 = *(const float4*)(sp + 0 * 64); Pw1 = *(const float4*)(sp + 1 * 64); Pk1 = *(const float4*)(sp + 2 * 64); Pa1 = *(const float4*)(sp + 4 * 64); Pb1 = *(const float4*)(sp + 5 * 64); Pv1 = vp[0]; }
;           else { Pr0 = *(const float4*)(sp + 0 * 64); Pw0 = *(const float4*)(sp + 1 * 64); Pk0 = *(const float4*)(sp + 2 * 64); Pa0 = *(const float4*)(sp + 4 * 64); Pb0 = *(const float4*)(sp + 5 * 64); Pv0 = vp[0]; }
;         }
;         const fv2 a01 = {ca.x, ca.y}, a23 = {ca.z, ca.w}, w01 = {cw.x, cw.y}, w23 = {cw.z, cw.w};
;         const fv2 k01 = {ck.x, ck.y}, k23 = {ck.z, ck.w}, b01 = {cb.x, cb.y}, b23 = {cb.z, cb.w};
;         const fv2 r01 = {cr.x, cr.y}, r23 = {cr.z, cr.w};
;         const fv2 vv = {cv, cv};
;         fv2 pa = S01 * a01; pa = __builtin_elementwise_fma(S23, a23, pa);
;         float sa = pa.x + pa.y;
;         const fv2 t01 = __builtin_elementwise_fma(S01, w01, vv * k01);
;         const fv2 t23 = __builtin_elementwise_fma(S23, w23, vv * k23);
;         sa = row16_sum(sa);
;         const fv2 sav = {sa, sa};
;         S01 = __builtin_elementwise_fma(sav, b01, t01);
;         S23 = __builtin_elementwise_fma(sav, b23, t23);
;         fv2 py = S01 * r01; py = __builtin_elementwise_fma(S23, r23, py);
;         ypart[(ch & 1) * 4096 + s * 256 + tid] = py.x + py.y;
	v_pk_mul_f32 v[118:119], v[64:65], v[50:51]
	v_pk_mul_f32 v[46:47], v[46:47], v[62:63] op_sel:[0,1] op_sel_hi:[1,1]
	v_pk_fma_f32 v[118:119], v[66:67], v[52:53], v[118:119]
	v_pk_mul_f32 v[48:49], v[48:49], v[62:63] op_sel:[0,1] op_sel_hi:[1,1]
	v_pk_fma_f32 v[42:43], v[64:65], v[42:43], v[46:47]
	v_add_f32_e32 v118, v118, v119
	v_pk_fma_f32 v[44:45], v[66:67], v[44:45], v[48:49]
	v_pk_mul_f32 v[120:121], v[64:65], v[14:15]
	v_add_f32_dpp v118, v118, v118 quad_perm:[1,0,3,2] row_mask:0xf bank_mask:0xf bound_ctrl:1
	v_pk_fma_f32 v[120:121], v[66:67], v[16:17], v[120:121]
	ds_read_b128 v[108:111], v124 offset:24064
	v_add_f32_dpp v118, v118, v118 quad_perm:[2,3,0,1] row_mask:0xf bank_mask:0xf bound_ctrl:1
	v_add_f32_e32 v122, v120, v121
	ds_read_b128 v[104:107], v124 offset:23552
	v_add_f32_dpp v118, v118, v118 row_half_mirror row_mask:0xf bank_mask:0xf bound_ctrl:1
	ds_read_b128 v[100:103], v124 offset:23296
	ds_read_b128 v[112:115], v124 offset:24320
	v_add_f32_dpp v118, v118, v118 row_mirror row_mask:0xf bank_mask:0xf bound_ctrl:1
	v_pk_fma_f32 v[64:65], v[118:119], v[38:39], v[42:43] op_sel_hi:[0,1,1]
	v_pk_fma_f32 v[66:67], v[118:119], v[40:41], v[44:45] op_sel_hi:[0,1,1]
	ds_read_b128 v[96:99], v124 offset:23040
	s_waitcnt lgkmcnt(6)
	v_pk_mul_f32 v[118:119], v[64:65], v[88:89]
	v_pk_mul_f32 v[84:85], v[84:85], v[116:117] op_sel_hi:[1,0]
	v_pk_fma_f32 v[118:119], v[66:67], v[90:91], v[118:119]
	v_pk_mul_f32 v[86:87], v[86:87], v[116:117] op_sel_hi:[1,0]
	v_pk_fma_f32 v[80:81], v[64:65], v[80:81], v[84:85]
	v_add_f32_e32 v118, v118, v119
	v_pk_fma_f32 v[82:83], v[66:67], v[82:83], v[86:87]
	v_pk_mul_f32 v[120:121], v[64:65], v[34:35]
	v_add_f32_dpp v118, v118, v118 quad_perm:[1,0,3,2] row_mask:0xf bank_mask:0xf bound_ctrl:1
	v_pk_fma_f32 v[120:121], v[66:67], v[36:37], v[120:121]
	ds_read2st64_b32 v[62:63], v127 offset0:3 offset1:9
	v_add_f32_dpp v118, v118, v118 quad_perm:[2,3,0,1] row_mask:0xf bank_mask:0xf bound_ctrl:1
	v_add_f32_e32 v123, v120, v121
	ds_read_b128 v[26:29], v126 offset:1024
	v_add_f32_dpp v118, v118, v118 row_half_mirror row_mask:0xf bank_mask:0xf bound_ctrl:1
	ds_read_b128 v[22:25], v126 offset:512
	ds_read_b128 v[18:21], v126 offset:256
	v_add_f32_dpp v118, v118, v118 row_mirror row_mask:0xf bank_mask:0xf bound_ctrl:1
	v_pk_fma_f32 v[64:65], v[118:119], v[92:93], v[80:81] op_sel_hi:[0,1,1]
	v_pk_fma_f32 v[66:67], v[118:119], v[94:95], v[82:83] op_sel_hi:[0,1,1]
	ds_read_b128 v[30:33], v126 offset:1280
	ds_read_b128 v[14:17], v126
	ds_write2st64_b32 v128, v122, v123 offset0:48 offset1:52
	s_waitcnt lgkmcnt(7)
	v_pk_mul_f32 v[118:119], v[64:65], v[108:109]
	v_pk_mul_f32 v[104:105], v[104:105], v[116:117] op_sel:[0,1] op_sel_hi:[1,1]
	v_pk_fma_f32 v[118:119], v[66:67], v[110:111], v[118:119]
	v_pk_mul_f32 v[106:107], v[106:107], v[116:117] op_sel:[0,1] op_sel_hi:[1,1]
	v_pk_fma_f32 v[100:101], v[64:65], v[100:101], v[104:105]
	v_add_f32_e32 v118, v118, v119
	v_pk_fma_f32 v[102:103], v[66:67], v[102:103], v[106:107]
	v_pk_mul_f32 v[120:121], v[64:65], v[76:77]
	v_add_f32_dpp v118, v118, v118 quad_perm:[1,0,3,2] row_mask:0xf bank_mask:0xf bound_ctrl:1
	v_pk_fma_f32 v[120:121], v[66:67], v[78:79], v[120:121]
	ds_read_b128 v[50:53], v126 offset:2560
	v_add_f32_dpp v118, v118, v118 quad_perm:[2,3,0,1] row_mask:0xf bank_mask:0xf bound_ctrl:1
	v_add_f32_e32 v122, v120, v121
	ds_read_b128 v[46:49], v126 offset:2048
	v_add_f32_dpp v118, v118, v118 row_half_mirror row_mask:0xf bank_mask:0xf bound_ctrl:1
	ds_read_b128 v[42:45], v126 offset:1792
	ds_read_b128 v[38:41], v126 offset:2816
	v_add_f32_dpp v118, v118, v118 row_mirror row_mask:0xf bank_mask:0xf bound_ctrl:1
	v_pk_fma_f32 v[64:65], v[118:119], v[112:113], v[100:101] op_sel_hi:[0,1,1]
	v_pk_fma_f32 v[66:67], v[118:119], v[114:115], v[102:103] op_sel_hi:[0,1,1]
	ds_read_b128 v[34:37], v126 offset:1536
	v_pk_mul_f32 v[120:121], v[64:65], v[96:97]
	v_pk_fma_f32 v[120:121], v[66:67], v[98:99], v[120:121]
	v_add_f32_e32 v123, v120, v121
	ds_write2st64_b32 v128, v122, v123 offset0:56 offset1:60
	s_branch .LBB0_498

; #define MFMA32(a, b, c) __builtin_amdgcn_mfma_f32_32x32x16_bf16((a), (b), (c), 0, 0, 0)
; DI int crow(int i, int h) { return (i & 3) + 8 * (i >> 2) + 4 * h; }
; template <int MODE> ...
;     ...
;     for (int kt = 0; kt < 2; ++kt) {
; #pragma unroll
;       for (int e = 0; e < 16; ++e) s[kt][e] = 0.f;
; #pragma unroll
;       for (int si = 0; si < 4; ++si) {
;         const bf16x8 fa = *(const bf16x8*)(Ks + (32 * kt + r31) * LDT + 16 * si + 8 * h);
;         s[kt] = MFMA32(fa, qf[si], s[kt]);
;       }
;     }
;     const bool selj = (MODE == 1) ? (((sel >> j) & 1) != 0) : true;
;     const bool interior = (MODE == 1) ? (64 * j + 63 <= qmin) : (MODE == 2) ? ((64 * j + 63 <= qmin) && (qmax - 64 * j < W)) : false;
;     float mx = -1e30f;
;     if (interior) {
; #pragma unroll
;       for (int kt = 0; kt < 2; ++kt)
; #pragma unroll
;         for (int e = 0; e < 16; ++e) {
;           const float v = (MODE == 1) ? (selj ? s[kt][e] : -1e30f) : s[kt][e];
;           s[kt][e] = v; mx = fmaxf(mx, v);
;         }
;     } else {
; #pragma unroll
;       for (int kt = 0; kt < 2; ++kt)
; #pragma unroll
;         for (int e = 0; e < 16; ++e) {
;           const int key = 64 * j + 32 * kt + crow(e, h);
;           bool valid;
;           if (MODE == 0) valid = (16 * key + 31 <= qpos);
;           else if (MODE == 1) valid = selj && (key <= qpos);
;           else valid = (key <= qpos) && (qpos - key < W);
;           const float v = valid ? s[kt][e] : -1e30f;
;           s[kt][e] = v; mx = fmaxf(mx, v);
;         }
.LBB0_613:
	s_mov_b64 s[6:7], -1
	v_add_u32_e32 v0, v217, v239
	ds_read_b128 v[2:5], v0
	ds_read_b128 v[6:9], v0 offset:32
	ds_read_b128 v[128:131], v0 offset:64
	ds_read_b128 v[132:135], v0 offset:96
	ds_read_b128 v[136:139], v0 offset:4608
	ds_read_b128 v[18:21], v0 offset:4640
	ds_read_b128 v[140:143], v0 offset:4672
	ds_read_b128 v[144:147], v0 offset:4704
	s_lshl_b32 s9, s10, 6
	s_or_b32 s0, s9, 63
	s_cmp_le_i32 s0, s23
	s_cselect_b64 s[2:3], -1, 0
	s_cmp_gt_i32 s0, s23
	s_waitcnt lgkmcnt(7)
	v_mfma_f32_32x32x16_bf16 v[160:175], v[2:5], v[176:179], 0
	s_waitcnt lgkmcnt(6)
	v_mfma_f32_32x32x16_bf16 v[160:175], v[6:9], v[180:183], v[160:175]
	s_waitcnt lgkmcnt(5)
	v_mfma_f32_32x32x16_bf16 v[160:175], v[128:131], v[184:187], v[160:175]
	v_lshrrev_b32_e32 v0, s10, v236
	v_and_b32_e32 v0, 1, v0
	s_waitcnt lgkmcnt(4)
	v_mfma_f32_32x32x16_bf16 v[160:175], v[132:135], v[188:191], v[160:175]
	v_cmp_eq_u32_e64 s[36:37], 1, v0
	s_waitcnt lgkmcnt(3)
	v_mfma_f32_32x32x16_bf16 v[2:17], v[136:139], v[176:179], 0
	s_waitcnt lgkmcnt(2)
	v_mfma_f32_32x32x16_bf16 v[2:17], v[18:21], v[180:183], v[2:17]
	s_waitcnt lgkmcnt(1)
	v_mfma_f32_32x32x16_bf16 v[2:17], v[140:143], v[184:187], v[2:17]
	s_waitcnt lgkmcnt(0)
	v_mfma_f32_32x32x16_bf16 v[2:17], v[144:147], v[188:191], v[2:17]
	s_cbranch_scc0 .LBB0_615
	v_or_b32_e32 v18, s9, v238
	v_cmp_le_i32_e32 vcc, v18, v212
	s_and_b64 vcc, s[36:37], vcc
	v_or_b32_e32 v19, 2, v18
	v_cndmask_b32_e32 v128, v229, v160, vcc
	v_cmp_lt_i32_e32 vcc, v18, v212
	s_and_b64 vcc, s[36:37], vcc
	v_max_f32_e32 v0, v128, v128
	v_cndmask_b32_e32 v129, v229, v161, vcc
	v_cmp_le_i32_e32 vcc, v19, v212
	s_and_b64 vcc, s[36:37], vcc
	v_or_b32_e32 v19, 3, v18
	v_cndmask_b32_e32 v130, v229, v162, vcc
	v_cmp_le_i32_e32 vcc, v19, v212
	s_and_b64 vcc, s[36:37], vcc
	v_or_b32_e32 v19, 8, v18
	v_cndmask_b32_e32 v131, v229, v163, vcc
	v_cmp_le_i32_e32 vcc, v19, v212
	s_and_b64 vcc, s[36:37], vcc
	v_or_b32_e32 v19, 9, v18
	v_cndmask_b32_e32 v132, v229, v164, vcc
	v_cmp_le_i32_e32 vcc, v19, v212
	s_and_b64 vcc, s[36:37], vcc
	v_or_b32_e32 v19, 10, v18
	v_cndmask_b32_e32 v133, v229, v165, vcc
	v_cmp_le_i32_e32 vcc, v19, v212
	s_and_b64 vcc, s[36:37], vcc
	v_or_b32_e32 v19, 11, v18
	v_cndmask_b32_e32 v134, v229, v166, vcc
	v_cmp_le_i32_e32 vcc, v19, v212
	s_and_b64 vcc, s[36:37], vcc
	v_or_b32_e32 v19, 16, v18
	v_cndmask_b32_e32 v135, v229, v167, vcc
	v_cmp_le_i32_e32 vcc, v19, v212
	s_and_b64 vcc, s[36:37], vcc
	v_or_b32_e32 v19, 17, v18
	v_cndmask_b32_e32 v136, v229, v168, vcc
	v_cmp_le_i32_e32 vcc, v19, v212
	s_and_b64 vcc, s[36:37], vcc
	v_or_b32_e32 v19, 18, v18
	v_cndmask_b32_e32 v137, v229, v169, vcc
	v_cmp_le_i32_e32 vcc, v19, v212
	s_and_b64 vcc, s[36:37], vcc
	v_or_b32_e32 v19, 19, v18
	v_cndmask_b32_e32 v138, v229, v170, vcc
	v_cmp_le_i32_e32 vcc, v19, v212
	s_and_b64 vcc, s[36:37], vcc
	v_or_b32_e32 v19, 24, v18
	v_cndmask_b32_e32 v139, v229, v171, vcc
	v_cmp_le_i32_e32 vcc, v19, v212
	s_and_b64 vcc, s[36:37], vcc
	v_or_b32_e32 v19, 25, v18
	v_cndmask_b32_e32 v140, v229, v172, vcc
	v_cmp_le_i32_e32 vcc, v19, v212
	s_and_b64 vcc, s[36:37], vcc
	v_or_b32_e32 v19, 26, v18
	v_cndmask_b32_e32 v141, v229, v173, vcc
	v_cmp_le_i32_e32 vcc, v19, v212
	s_and_b64 vcc, s[36:37], vcc
	v_or_b32_e32 v19, 27, v18
	v_cndmask_b32_e32 v142, v229, v174, vcc
	v_cmp_le_i32_e32 vcc, v19, v212
	s_and_b64 vcc, s[36:37], vcc
	v_or_b32_e32 v19, 32, v18
	v_cndmask_b32_e32 v143, v229, v175, vcc
	v_cmp_le_i32_e32 vcc, v19, v212
	s_and_b64 vcc, s[36:37], vcc
	v_or_b32_e32 v19, 33, v18
	v_cndmask_b32_e32 v144, v229, v2, vcc
	v_cmp_le_i32_e32 vcc, v19, v212
	s_and_b64 vcc, s[36:37], vcc
	v_or_b32_e32 v19, 34, v18
	v_cndmask_b32_e32 v145, v229, v3, vcc
	v_cmp_le_i32_e32 vcc, v19, v212
	s_and_b64 vcc, s[36:37], vcc
	v_or_b32_e32 v19, 35, v18
	v_cndmask_b32_e32 v146, v229, v4, vcc
	v_cmp_le_i32_e32 vcc, v19, v212
	s_and_b64 vcc, s[36:37], vcc
	v_or_b32_e32 v19, 40, v18
	v_cndmask_b32_e32 v147, v229, v5, vcc
	v_cmp_le_i32_e32 vcc, v19, v212
	s_and_b64 vcc, s[36:37], vcc
	v_or_b32_e32 v19, 41, v18
	v_cndmask_b32_e32 v148, v229, v6, vcc
	v_cmp_le_i32_e32 vcc, v19, v212
	s_and_b64 vcc, s[36:37], vcc
	v_or_b32_e32 v19, 42, v18
	v_cndmask_b32_e32 v149, v229, v7, vcc
	v_cmp_le_i32_e32 vcc, v19, v212
	s_and_b64 vcc, s[36:37], vcc
	v_or_b32_e32 v19, 43, v18
	v_cndmask_b32_e32 v150, v229, v8, vcc
	v_cmp_le_i32_e32 vcc, v19, v212
	s_and_b64 vcc, s[36:37], vcc
	v_or_b32_e32 v19, 48, v18
	v_max_f32_e32 v0, 0xf149f2ca, v0
	v_cndmask_b32_e32 v151, v229, v9, vcc
	v_cmp_le_i32_e32 vcc, v19, v212
	v_max3_f32 v0, v0, v129, v130
	s_and_b64 vcc, s[36:37], vcc
	v_or_b32_e32 v19, 49, v18
	v_max3_f32 v0, v0, v131, v132
	v_cndmask_b32_e32 v152, v229, v10, vcc
	v_cmp_le_i32_e32 vcc, v19, v212
	v_max3_f32 v0, v0, v133, v134
	s_and_b64 vcc, s[36:37], vcc
	v_or_b32_e32 v19, 50, v18
	v_max3_f32 v0, v0, v135, v136
	v_cndmask_b32_e32 v153, v229, v11, vcc
	v_cmp_le_i32_e32 vcc, v19, v212
	v_max3_f32 v0, v0, v137, v138
	s_and_b64 vcc, s[36:37], vcc
	v_or_b32_e32 v19, 51, v18
	v_max3_f32 v0, v0, v139, v140
	v_cndmask_b32_e32 v154, v229, v12, vcc
	v_cmp_le_i32_e32 vcc, v19, v212
	v_max3_f32 v0, v0, v141, v142
	s_and_b64 vcc, s[36:37], vcc
	v_or_b32_e32 v19, 56, v18
	v_max3_f32 v0, v0, v143, v144
	v_cndmask_b32_e32 v155, v229, v13, vcc
	v_cmp_le_i32_e32 vcc, v19, v212
	v_max3_f32 v0, v0, v145, v146
	s_and_b64 vcc, s[36:37], vcc
	v_or_b32_e32 v19, 57, v18
	v_max3_f32 v0, v0, v147, v148
	v_cndmask_b32_e32 v156, v229, v14, vcc
	v_cmp_le_i32_e32 vcc, v19, v212
	v_max3_f32 v0, v0, v149, v150
	s_and_b64 vcc, s[36:37], vcc
	v_or_b32_e32 v19, 58, v18
	v_max3_f32 v0, v0, v151, v152
	v_cndmask_b32_e32 v157, v229, v15, vcc
	v_cmp_le_i32_e32 vcc, v19, v212
	v_max3_f32 v0, v0, v153, v154
	s_and_b64 vcc, s[36:37], vcc
	v_or_b32_e32 v18, 59, v18
	v_max3_f32 v0, v0, v155, v156
	v_cndmask_b32_e32 v158, v229, v16, vcc
	v_cmp_le_i32_e32 vcc, v18, v212
	v_max3_f32 v0, v0, v157, v158
	s_and_b64 s[4:5], s[36:37], vcc
	s_mov_b64 s[6:7], 0

; #define MFMA32(a, b, c) __builtin_amdgcn_mfma_f32_32x32x16_bf16((a), (b), (c), 0, 0, 0)
; DI unsigned pack2(float a, float b) { fv2 v = {a, b}; return __builtin_bit_cast(unsigned, __builtin_convertvector(v, bfv2)); }
; template <int MODE> ...
;     ...
; #pragma unroll
;     for (int kt = 0; kt < 2; ++kt)
; #pragma unroll
;       for (int sp = 0; sp < 2; ++sp) {
;         const bf16x8 fb = __builtin_bit_cast(bf16x8, make_uint4(pack2(s[kt][8 * sp + 0], s[kt][8 * sp + 1]), pack2(s[kt][8 * sp + 2], s[kt][8 * sp + 3]),
;                                                                pack2(s[kt][8 * sp + 4], s[kt][8 * sp + 5]), pack2(s[kt][8 * sp + 6], s[kt][8 * sp + 7])));
; #pragma unroll
;         for (int dt = 0; dt < 2; ++dt) {
;           const bf16_t* vr = Vs + (32 * dt + r31) * LDT + 32 * kt + 16 * sp + 4 * h;
;           const uint2 lo = *(const uint2*)vr; const uint2 hi = *(const uint2*)(vr + 8);
;           const bf16x8 fa = __builtin_bit_cast(bf16x8, make_uint4(lo.x, lo.y, hi.x, hi.y));
;           o[dt] = MFMA32(fa, fb, o[dt]);
;         }
;       }
.LBB0_623:
	s_or_b64 exec, exec, s[2:3]
	v_add_u32_e32 v156, 0x2000, v240
	v_add_u32_e32 v157, 0x3000, v240
	ds_read2_b64 v[132:135], v156 offset0:128 offset1:130
	ds_read2_b64 v[136:139], v157 offset0:192 offset1:194
	ds_read2_b64 v[140:143], v156 offset0:132 offset1:134
	ds_read2_b64 v[144:147], v157 offset0:196 offset1:198
	ds_read2_b64 v[148:151], v156 offset0:136 offset1:138
	ds_read2_b64 v[152:155], v157 offset0:200 offset1:202
	v_cvt_pk_bf16_f32 v128, v0, v3
	v_cvt_pk_bf16_f32 v129, v2, v5
	v_cvt_pk_bf16_f32 v130, v4, v7
	v_cvt_pk_bf16_f32 v4, v12, v13
	v_cvt_pk_bf16_f32 v5, v14, v15
	v_cvt_pk_bf16_f32 v131, v6, v17
	v_cvt_pk_bf16_f32 v6, v16, v19
	v_cvt_pk_bf16_f32 v2, v8, v9
	v_cvt_pk_bf16_f32 v3, v10, v11
	v_cvt_pk_bf16_f32 v7, v18, v21
	v_cvt_pk_bf16_f32 v8, v20, v23
	v_cvt_pk_bf16_f32 v9, v22, v25
	v_cvt_pk_bf16_f32 v10, v24, v27
	v_cvt_pk_bf16_f32 v11, v26, v29
	v_cvt_pk_bf16_f32 v12, v28, v159
	v_cvt_pk_bf16_f32 v13, v30, v31
	s_xor_b64 s[0:1], s[40:41], -1
	s_and_b64 vcc, exec, s[0:1]
	s_waitcnt lgkmcnt(5)
	v_mfma_f32_32x32x16_bf16 v[96:111], v[132:135], v[128:131], v[96:111]
	s_waitcnt lgkmcnt(4)
	v_mfma_f32_32x32x16_bf16 v[112:127], v[136:139], v[128:131], v[112:127]
	ds_read2_b64 v[132:135], v156 offset0:140 offset1:142
	ds_read2_b64 v[136:139], v157 offset0:204 offset1:206
	s_waitcnt lgkmcnt(5)
	v_mfma_f32_32x32x16_bf16 v[96:111], v[140:143], v[2:5], v[96:111]
	s_waitcnt lgkmcnt(4)
	v_mfma_f32_32x32x16_bf16 v[112:127], v[144:147], v[2:5], v[112:127]
	s_waitcnt lgkmcnt(3)
	v_mfma_f32_32x32x16_bf16 v[96:111], v[148:151], v[6:9], v[96:111]
	s_waitcnt lgkmcnt(2)
	v_mfma_f32_32x32x16_bf16 v[112:127], v[152:155], v[6:9], v[112:127]
	s_waitcnt lgkmcnt(1)
	v_mfma_f32_32x32x16_bf16 v[96:111], v[132:135], v[10:13], v[96:111]
	s_waitcnt lgkmcnt(0)
	v_mfma_f32_32x32x16_bf16 v[112:127], v[136:139], v[10:13], v[112:127]
	s_cbranch_vccnz .LBB0_625
	v_mov_b32_e32 v241, v160
	s_mov_b32 s10, s8
	s_branch .LBB0_607

; __global__ void __launch_bounds__(512, 2) fwd_megakernel(Params p) {
	.amdhsa_kernel _Z14fwd_megakernel6Params
		.amdhsa_group_segment_fixed_size 0
		.amdhsa_private_segment_fixed_size 0
		.amdhsa_kernarg_size 504
		.amdhsa_user_sgpr_count 2
		.amdhsa_user_sgpr_dispatch_ptr 0
		.amdhsa_user_sgpr_queue_ptr 0
		.amdhsa_user_sgpr_kernarg_segment_ptr 1
		.amdhsa_user_sgpr_dispatch_id 0
		.amdhsa_user_sgpr_kernarg_preload_length 0
		.amdhsa_user_sgpr_kernarg_preload_offset 0
		.amdhsa_user_sgpr_private_segment_size 0
		.amdhsa_uses_dynamic_stack 0
		.amdhsa_enable_private_segment 0
		.amdhsa_system_sgpr_workgroup_id_x 1
		.amdhsa_system_sgpr_workgroup_id_y 0
		.amdhsa_system_sgpr_workgroup_id_z 0
		.amdhsa_system_sgpr_workgroup_info 0
		.amdhsa_system_vgpr_workitem_id 2
		.amdhsa_next_free_vgpr 253
		.amdhsa_next_free_sgpr 102
		.amdhsa_accum_offset 256
		.amdhsa_reserve_vcc 1
		.amdhsa_float_round_mode_32 0
		.amdhsa_float_round_mode_16_64 0
		.amdhsa_float_denorm_mode_32 3
		.amdhsa_float_denorm_mode_16_64 3
		.amdhsa_dx10_clamp 1
		.amdhsa_ieee_mode 1
		.amdhsa_fp16_overflow 0
		.amdhsa_tg_split 0
		.amdhsa_exception_fp_ieee_invalid_op 0
		.amdhsa_exception_fp_denorm_src 0
		.amdhsa_exception_fp_ieee_div_zero 0
		.amdhsa_exception_fp_ieee_overflow 0
		.amdhsa_exception_fp_ieee_underflow 0
		.amdhsa_exception_fp_ieee_inexact 0
		.amdhsa_exception_int_div_zero 0
	.end_amdhsa_kernel

; __global__ void __launch_bounds__(512, 2) fwd_megakernel(Params p) {
amdhsa.kernels:
  - .agpr_count:     0
    .args:
      - .offset:         0
        .size:           248
        .value_kind:     by_value
      - .offset:         248
        .size:           4
        .value_kind:     hidden_block_count_x
      - .offset:         252
        .size:           4
        .value_kind:     hidden_block_count_y
      - .offset:         256
        .size:           4
        .value_kind:     hidden_block_count_z
      - .offset:         260
        .size:           2
        .value_kind:     hidden_group_size_x
      - .offset:         262
        .size:           2
        .value_kind:     hidden_group_size_y
      - .offset:         264
        .size:           2
        .value_kind:     hidden_group_size_z
      - .offset:         266
        .size:           2
        .value_kind:     hidden_remainder_x
      - .offset:         268
        .size:           2
        .value_kind:     hidden_remainder_y
      - .offset:         270
        .size:           2
        .value_kind:     hidden_remainder_z
      - .offset:         288
        .size:           8
        .value_kind:     hidden_global_offset_x
      - .offset:         296
        .size:           8
        .value_kind:     hidden_global_offset_y
      - .offset:         304
        .size:           8
        .value_kind:     hidden_global_offset_z
      - .offset:         312
        .size:           2
        .value_kind:     hidden_grid_dims
      - .offset:         336
        .size:           8
        .value_kind:     hidden_multigrid_sync_arg
      - .offset:         368
        .size:           4
        .value_kind:     hidden_dynamic_lds_size
    .group_segment_fixed_size: 0
    .kernarg_segment_align: 8
    .kernarg_segment_size: 504
    .language:       OpenCL C
    .language_version:
      - 2
      - 0
    .max_flat_workgroup_size: 512
    .name:           _Z14fwd_megakernel6Params
    .private_segment_fixed_size: 0
    .sgpr_count:     108
    .sgpr_spill_count: 111
    .symbol:         _Z14fwd_megakernel6Params.kd
    .uniform_work_group_size: 1
    .uses_dynamic_stack: false
    .vgpr_count:     253
    .vgpr_spill_count: 0
    .wavefront_size: 64
